# peer_q: second key-half's first tiles (token rows x2, key tile DMA) are issued before the first half's top-k instead of after it
# speedup vs baseline: 1.0563x; 1.0064x over previous
; #define tid_opaque() tid_from(WAVE_S)
;   const int tid = tid_opaque(), lane = tid & 63;
;   u16* Xs = lds;
;   u16* Ys = lds + 128 * LSTR;
;   const int lr = tid >> 3, lc = (tid & 7) * 8;
;   const u16* xg = X + (size_t)lr * RS + lc;
;   const u16* yg = Y + (size_t)lr * RS + lc;
;   u32x4 xr[4], yr[4];
; #pragma unroll
;   for (int it = 0; it < 4; ++it) {
;     xr[it] = *(const u32x4*)(xg + (size_t)it * 32 * RS);
;     yr[it] = *(const u32x4*)(yg + (size_t)it * 32 * RS);
;   }
; #pragma unroll
;   for (int a = 0; a < TI; ++a)
; #pragma unroll
;     for (int b = 0; b < TJ; ++b)
; #pragma unroll
;       for (int r = 0; r < 16; ++r) acc[a][b][r] = 0.f;
.LBB0_390:
	s_or_b32 s28, s19, s18
	v_mbcnt_lo_u32_b32 v12, -1, 0
	v_mbcnt_hi_u32_b32 v12, -1, v12
	s_xor_b64 s[46:47], s[48:49], -1
	v_add_u32_e32 v0, s33, v12
	s_lshl_b64 s[50:51], s[28:29], 1
	v_ashrrev_i32_e32 v2, 3, v0
	s_add_u32 s50, s84, s50
	v_ashrrev_i32_e32 v3, 31, v2
	s_addc_u32 s51, s85, s51
	v_lshlrev_b64 v[4:5], 11, v[2:3]
	v_lshlrev_b32_e32 v0, 4, v12
	v_lshl_add_u64 v[6:7], s[50:51], 0, v[4:5]
	v_and_b32_e32 v0, 0x70, v0
	s_mov_b32 s100, s50
	s_mov_b32 s101, s51
	s_lshr_b32 vcc_lo, s33, 7
	s_lshl_b32 vcc_lo, vcc_lo, 5
	s_lshr_b32 s32, s33, 6
	s_lshl_b32 s32, s32, 12
	s_add_u32 s41, s32, 0x8000
	s_add_u32 s41, s41, vcc_lo
	s_lshr_b32 vcc_lo, s33, 1
	v_lshrrev_b32_e32 v135, 3, v12
	v_add_u32_e32 v135, vcc_lo, v135
	v_lshlrev_b32_e32 v135, 11, v135
	v_and_b32_e32 v136, 7, v12
	v_lshrrev_b32_e32 v137, 4, v12
	v_xor_b32_e32 v136, v136, v137
	v_lshl_add_u32 v120, v136, 4, v135
	v_and_b32_e32 v134, 7, v12
	v_lshl_add_u32 v119, v134, 4, v135
	v_lshrrev_b32_e32 v134, 3, v12
	v_lshlrev_b32_e32 v134, 7, v134
	v_lshl_add_u32 v118, v136, 4, v134
	v_add_u32_e32 v118, s32, v118
	v_xor_b32_e32 v136, 4, v136
	v_lshl_add_u32 v121, v136, 4, v135
	v_add_u32_e32 v121, 0x3c00, v121
	v_and_b32_e32 v138, 31, v12
	v_lshlrev_b32_e32 v138, 7, v138
	v_bfe_u32 v139, v12, 1, 3
	v_lshrrev_b32_e32 v140, 5, v12
	v_xor_b32_e32 v139, v139, v140
	v_xor_b32_e32 v141, 0, v139
	v_lshl_add_u32 v114, v141, 4, v138
	v_xor_b32_e32 v141, 2, v139
	v_lshl_add_u32 v115, v141, 4, v138
	v_xor_b32_e32 v141, 4, v139
	v_lshl_add_u32 v116, v141, 4, v138
	v_xor_b32_e32 v141, 6, v139
	v_lshl_add_u32 v117, v141, 4, v138
	v_lshl_add_u64 v[6:7], v[6:7], 0, v[0:1]
	v_lshl_add_u64 v[8:9], s[44:45], 0, v[4:5]
	s_nop 0
	v_add_co_u32_e32 v8, vcc, s81, v6
	s_cmp_lg_u64 s[46:47], 0
	s_cbranch_scc1 .Lpq_skipld
	global_load_dwordx4 v[70:73], v119, s[44:45]
	v_add_u32_e32 v133, 0x4000, v119
	global_load_dwordx4 v[78:81], v133, s[44:45]
	v_add_u32_e32 v133, 0x8000, v119
	global_load_dwordx4 v[86:89], v133, s[44:45]
	v_add_u32_e32 v133, 0xc000, v119
	global_load_dwordx4 v[94:97], v133, s[44:45]
	s_mov_b32 m0, s32
	s_nop 0
	global_load_lds_dwordx4 v120, s[100:101]
	global_load_lds_dwordx4 v121, s[100:101] offset:1024
	v_add_u32_e32 v133, 0x7800, v120
	global_load_lds_dwordx4 v133, s[100:101] offset:2048
	v_add_u32_e32 v133, 0x7800, v121
	global_load_lds_dwordx4 v133, s[100:101] offset:3072
	global_load_dwordx4 v[66:69], v119, s[44:45] offset:128
	v_add_u32_e32 v133, 0x4000, v119
	global_load_dwordx4 v[74:77], v133, s[44:45] offset:128
	v_add_u32_e32 v133, 0x8000, v119
	global_load_dwordx4 v[82:85], v133, s[44:45] offset:128
	v_add_u32_e32 v133, 0xc000, v119
	global_load_dwordx4 v[90:93], v133, s[44:45] offset:128
.Lpq_skipld:
	v_addc_co_u32_e32 v9, vcc, 0, v7, vcc
	v_add_co_u32_e32 v10, vcc, s81, v116
	v_and_b32_e32 v3, 31, v12
	s_nop 0
	v_addc_co_u32_e32 v11, vcc, 0, v117, vcc
	v_add_co_u32_e32 v8, vcc, s12, v6
	s_nop 0
	s_nop 0
	v_addc_co_u32_e32 v9, vcc, 0, v7, vcc
	v_add_co_u32_e32 v10, vcc, s12, v116
	s_add_i32 s28, s18, s19
	s_nop 0
	v_addc_co_u32_e32 v11, vcc, 0, v117, vcc
	v_add_co_u32_e32 v6, vcc, s86, v6
	v_addc_co_u32_e32 v7, vcc, 0, v7, vcc
	v_add_co_u32_e32 v8, vcc, s86, v116
	v_and_b32_e32 v0, 7, v12
	s_nop 0
	v_addc_co_u32_e32 v9, vcc, 0, v117, vcc
	v_lshrrev_b32_e32 v6, 1, v12
	v_and_b32_e32 v6, 16, v6
	v_or_b32_e32 v7, v3, v122
	s_nop 0
	s_lshl_b64 s[50:51], s[28:29], 1
	s_add_u32 s50, s96, s50
	v_mul_u32_u24_e32 v3, 0x90, v3
	v_lshl_or_b32 v4, v0, 4, v4
	s_addc_u32 s51, s97, s51
	v_mov_b32_e32 v2, 0
	s_nop 0
	s_mov_b64 s[50:51], s[44:45]
	s_nop 0
	v_mov_b32_e32 v3, v2
	v_mov_b32_e32 v4, v2
	v_mov_b32_e32 v5, v2
	v_mov_b32_e32 v6, v2
	v_mov_b32_e32 v7, v2
	v_mov_b32_e32 v8, v2
	v_mov_b32_e32 v9, v2
	v_mov_b32_e32 v10, v2
	v_mov_b32_e32 v11, v2
	v_mov_b32_e32 v12, v2
	v_mov_b32_e32 v13, v2
	v_mov_b32_e32 v14, v2
	v_mov_b32_e32 v15, v2
	v_mov_b32_e32 v16, v2
	v_mov_b32_e32 v17, v2
	v_mov_b32_e32 v18, v2
	v_mov_b32_e32 v19, v2
	v_mov_b32_e32 v20, v2
	v_mov_b32_e32 v21, v2
	v_mov_b32_e32 v22, v2
	v_mov_b32_e32 v23, v2
	v_mov_b32_e32 v24, v2
	v_mov_b32_e32 v25, v2
	v_mov_b32_e32 v26, v2
	v_mov_b32_e32 v27, v2
	v_mov_b32_e32 v28, v2
	v_mov_b32_e32 v29, v2
	v_mov_b32_e32 v30, v2
	v_mov_b32_e32 v31, v2
	v_mov_b32_e32 v32, v2
	v_mov_b32_e32 v33, v2
	s_waitcnt vmcnt(12)
	v_mov_b32_e32 v34, v2
	v_mov_b32_e32 v35, v2
	v_mov_b32_e32 v36, v2
	v_mov_b32_e32 v37, v2
	s_waitcnt vmcnt(8)
	v_mov_b32_e32 v38, v2
	v_mov_b32_e32 v39, v2
	v_mov_b32_e32 v40, v2
	v_mov_b32_e32 v41, v2
	v_mov_b32_e32 v42, v2
	v_mov_b32_e32 v43, v2
	v_mov_b32_e32 v44, v2
	v_mov_b32_e32 v45, v2
	v_mov_b32_e32 v46, v2
	v_mov_b32_e32 v47, v2
	v_mov_b32_e32 v48, v2
	v_mov_b32_e32 v49, v2
	v_mov_b32_e32 v50, v2
	v_mov_b32_e32 v51, v2
	v_mov_b32_e32 v52, v2
	v_mov_b32_e32 v53, v2
	s_waitcnt vmcnt(8)
	v_mov_b32_e32 v54, v2
	v_mov_b32_e32 v55, v2
	v_mov_b32_e32 v56, v2
	v_mov_b32_e32 v57, v2
	v_mov_b32_e32 v58, v2
	v_mov_b32_e32 v59, v2
	v_mov_b32_e32 v60, v2
	v_mov_b32_e32 v61, v2
	v_mov_b32_e32 v62, v2
	v_mov_b32_e32 v63, v2
	v_mov_b32_e32 v64, v2
	v_mov_b32_e32 v65, v2
	s_movk_i32 s19, 7
; #define MFMA32(a, b, c) __builtin_amdgcn_mfma_f32_32x32x16_bf16((a), (b), (c), 0, 0, 0)
;     ...
;   for (int kt = 0; kt < NKT; ++kt) {
;     __syncthreads();
; #pragma unroll
;     for (int it = 0; it < 4; ++it) {
;       *(u32x4*)(Xs + (lr + 32 * it) * LSTR + lc) = xr[it];
;       *(u32x4*)(Ys + (lr + 32 * it) * LSTR + lc) = yr[it];
;     }
;     __syncthreads();
;     if (kt + 1 < NKT) {
; #pragma unroll
;       for (int it = 0; it < 4; ++it) {
;         xr[it] = *(const u32x4*)(xg + (size_t)it * 32 * RS + (kt + 1) * 64);
;         yr[it] = *(const u32x4*)(yg + (size_t)it * 32 * RS + (kt + 1) * 64);
;       }
;     }
; #pragma unroll
;     for (int ks = 0; ks < 4; ++ks) {
;       bf16x8 af[TI], bfr[TJ];
; #pragma unroll
;       for (int a = 0; a < TI; ++a) af[a] = *(const bf16x8*)(Xs + (wi0 + a * 32 + fr) * LSTR + ks * 16 + fh);
; #pragma unroll
;       for (int b = 0; b < TJ; ++b) bfr[b] = *(const bf16x8*)(Ys + (wj0 + b * 32 + fr) * LSTR + ks * 16 + fh);
; #pragma unroll
;       for (int a = 0; a < TI; ++a)
; #pragma unroll
;         for (int b = 0; b < TJ; ++b) acc[a][b] = MFMA32(af[a], bfr[b], acc[a][b]);
;     }
;     __builtin_amdgcn_iglp_opt(1);
;   }
.Lwd_k_pq4:
	v_xor_b32_e32 v133, 0x40, v118
	s_waitcnt vmcnt(11)
	ds_write_b128 v118, v[70:73] offset:16384
	s_waitcnt vmcnt(10)
	ds_write_b128 v133, v[78:81] offset:17408
	s_waitcnt vmcnt(9)
	ds_write_b128 v118, v[86:89] offset:18432
	s_waitcnt vmcnt(8)
	ds_write_b128 v133, v[94:97] offset:19456
	s_waitcnt vmcnt(4)
	s_waitcnt lgkmcnt(0)
	s_barrier
	s_add_u32 s100, s100, 0x80
	s_addc_u32 s101, s101, 0
	s_mov_b32 m0, s41
	s_nop 0
	global_load_lds_dwordx4 v120, s[100:101]
	global_load_lds_dwordx4 v121, s[100:101] offset:1024
	v_add_u32_e32 v133, 0x7800, v120
	global_load_lds_dwordx4 v133, s[100:101] offset:2048
	v_add_u32_e32 v133, 0x7800, v121
	global_load_lds_dwordx4 v133, s[100:101] offset:3072
	ds_read_b128 v[134:137], v114 offset:4096
	ds_read_b128 v[138:141], v114 offset:8192
	ds_read_b128 v[142:145], v114 offset:12288
	ds_read_b128 v[148:151], v114
	ds_read_b128 v[152:155], v115
	v_add_u32_e32 v0, s32, v114
	ds_read_b128 v[160:163], v0 offset:16384
	v_add_u32_e32 v0, s32, v115
	ds_read_b128 v[156:159], v0 offset:16384
	s_waitcnt lgkmcnt(1)
	v_mfma_f32_32x32x16_bf16 v[34:49], v[134:137], v[160:163], v[34:49]
	ds_read_b128 v[134:137], v115 offset:4096
	v_mfma_f32_32x32x16_bf16 v[18:33], v[138:141], v[160:163], v[18:33]
	ds_read_b128 v[138:141], v115 offset:8192
	v_mfma_f32_32x32x16_bf16 v[2:17], v[142:145], v[160:163], v[2:17]
	ds_read_b128 v[142:145], v115 offset:12288
	s_waitcnt lgkmcnt(2)
	v_mfma_f32_32x32x16_bf16 v[34:49], v[134:137], v[156:159], v[34:49]
	ds_read_b128 v[134:137], v116
	s_waitcnt lgkmcnt(2)
	v_mfma_f32_32x32x16_bf16 v[18:33], v[138:141], v[156:159], v[18:33]
	ds_read_b128 v[138:141], v116 offset:4096
	s_waitcnt lgkmcnt(2)
	v_mfma_f32_32x32x16_bf16 v[2:17], v[142:145], v[156:159], v[2:17]
	ds_read_b128 v[142:145], v116 offset:8192
	v_mfma_f32_32x32x16_bf16 v[50:65], v[148:151], v[160:163], v[50:65]
	ds_read_b128 v[148:151], v116 offset:12288
	v_mfma_f32_32x32x16_bf16 v[50:65], v[152:155], v[156:159], v[50:65]
	v_add_u32_e32 v0, s32, v116
	ds_read_b128 v[152:155], v0 offset:16384
	s_waitcnt lgkmcnt(0)
	v_mfma_f32_32x32x16_bf16 v[50:65], v[134:137], v[152:155], v[50:65]
	ds_read_b128 v[134:137], v117
	v_mfma_f32_32x32x16_bf16 v[34:49], v[138:141], v[152:155], v[34:49]
	ds_read_b128 v[138:141], v117 offset:4096
	v_mfma_f32_32x32x16_bf16 v[18:33], v[142:145], v[152:155], v[18:33]
	ds_read_b128 v[142:145], v117 offset:8192
	v_mfma_f32_32x32x16_bf16 v[2:17], v[148:151], v[152:155], v[2:17]
	ds_read_b128 v[148:151], v117 offset:12288
	v_add_u32_e32 v0, s32, v117
	ds_read_b128 v[152:155], v0 offset:16384
	s_add_u32 s50, s50, 0x80
	s_addc_u32 s51, s51, 0
	global_load_dwordx4 v[70:73], v119, s[50:51] offset:128
	v_add_u32_e32 v133, 0x4000, v119
	global_load_dwordx4 v[78:81], v133, s[50:51] offset:128
	v_add_u32_e32 v133, 0x8000, v119
	global_load_dwordx4 v[86:89], v133, s[50:51] offset:128
	v_add_u32_e32 v133, 0xc000, v119
	global_load_dwordx4 v[94:97], v133, s[50:51] offset:128
	s_waitcnt lgkmcnt(0)
	v_mfma_f32_32x32x16_bf16 v[50:65], v[134:137], v[152:155], v[50:65]
	v_mfma_f32_32x32x16_bf16 v[34:49], v[138:141], v[152:155], v[34:49]
	v_mfma_f32_32x32x16_bf16 v[18:33], v[142:145], v[152:155], v[18:33]
	v_mfma_f32_32x32x16_bf16 v[2:17], v[148:151], v[152:155], v[2:17]
	v_xor_b32_e32 v133, 0x40, v118
	s_waitcnt vmcnt(11)
	ds_write_b128 v118, v[66:69] offset:16384
	s_waitcnt vmcnt(10)
	ds_write_b128 v133, v[74:77] offset:17408
	s_waitcnt vmcnt(9)
	ds_write_b128 v118, v[82:85] offset:18432
	s_waitcnt vmcnt(8)
	ds_write_b128 v133, v[90:93] offset:19456
	s_waitcnt vmcnt(4)
	s_waitcnt lgkmcnt(0)
	s_barrier
	s_add_u32 s100, s100, 0x80
	s_addc_u32 s101, s101, 0
	s_mov_b32 m0, s32
	s_nop 0
	global_load_lds_dwordx4 v120, s[100:101]
	global_load_lds_dwordx4 v121, s[100:101] offset:1024
	v_add_u32_e32 v133, 0x7800, v120
	global_load_lds_dwordx4 v133, s[100:101] offset:2048
	v_add_u32_e32 v133, 0x7800, v121
	global_load_lds_dwordx4 v133, s[100:101] offset:3072
	ds_read_b128 v[134:137], v114 offset:36864
	ds_read_b128 v[138:141], v114 offset:40992
	ds_read_b128 v[142:145], v114 offset:45088
	ds_read_b128 v[148:151], v114 offset:32768
	ds_read_b128 v[152:155], v115 offset:32768
	v_add_u32_e32 v0, s32, v114
	ds_read_b128 v[160:163], v0 offset:16384
	v_add_u32_e32 v0, s32, v115
	ds_read_b128 v[156:159], v0 offset:16384
	s_waitcnt lgkmcnt(1)
	v_mfma_f32_32x32x16_bf16 v[34:49], v[134:137], v[160:163], v[34:49]
	ds_read_b128 v[134:137], v115 offset:36864
	v_mfma_f32_32x32x16_bf16 v[18:33], v[138:141], v[160:163], v[18:33]
	ds_read_b128 v[138:141], v115 offset:40992
	v_mfma_f32_32x32x16_bf16 v[2:17], v[142:145], v[160:163], v[2:17]
	ds_read_b128 v[142:145], v115 offset:45088
	s_waitcnt lgkmcnt(2)
	v_mfma_f32_32x32x16_bf16 v[34:49], v[134:137], v[156:159], v[34:49]
	ds_read_b128 v[134:137], v116 offset:32768
	s_waitcnt lgkmcnt(2)
	v_mfma_f32_32x32x16_bf16 v[18:33], v[138:141], v[156:159], v[18:33]
	ds_read_b128 v[138:141], v116 offset:36864
	s_waitcnt lgkmcnt(2)
	v_mfma_f32_32x32x16_bf16 v[2:17], v[142:145], v[156:159], v[2:17]
	ds_read_b128 v[142:145], v116 offset:40992
	v_mfma_f32_32x32x16_bf16 v[50:65], v[148:151], v[160:163], v[50:65]
	ds_read_b128 v[148:151], v116 offset:45088
	v_mfma_f32_32x32x16_bf16 v[50:65], v[152:155], v[156:159], v[50:65]
	v_add_u32_e32 v0, s32, v116
	ds_read_b128 v[152:155], v0 offset:16384
	s_waitcnt lgkmcnt(0)
	v_mfma_f32_32x32x16_bf16 v[50:65], v[134:137], v[152:155], v[50:65]
	ds_read_b128 v[134:137], v117 offset:32768
	v_mfma_f32_32x32x16_bf16 v[34:49], v[138:141], v[152:155], v[34:49]
	ds_read_b128 v[138:141], v117 offset:36864
	v_mfma_f32_32x32x16_bf16 v[18:33], v[142:145], v[152:155], v[18:33]
	ds_read_b128 v[142:145], v117 offset:40992
	v_mfma_f32_32x32x16_bf16 v[2:17], v[148:151], v[152:155], v[2:17]
	ds_read_b128 v[148:151], v117 offset:45088
	v_add_u32_e32 v0, s32, v117
	ds_read_b128 v[152:155], v0 offset:16384
	s_add_u32 s50, s50, 0x80
	s_addc_u32 s51, s51, 0
	global_load_dwordx4 v[66:69], v119, s[50:51] offset:128
	v_add_u32_e32 v133, 0x4000, v119
	global_load_dwordx4 v[74:77], v133, s[50:51] offset:128
	v_add_u32_e32 v133, 0x8000, v119
	global_load_dwordx4 v[82:85], v133, s[50:51] offset:128
	v_add_u32_e32 v133, 0xc000, v119
	global_load_dwordx4 v[90:93], v133, s[50:51] offset:128
	s_waitcnt lgkmcnt(0)
	v_mfma_f32_32x32x16_bf16 v[50:65], v[134:137], v[152:155], v[50:65]
	v_mfma_f32_32x32x16_bf16 v[34:49], v[138:141], v[152:155], v[34:49]
	v_mfma_f32_32x32x16_bf16 v[18:33], v[142:145], v[152:155], v[18:33]
	v_mfma_f32_32x32x16_bf16 v[2:17], v[148:151], v[152:155], v[2:17]
	s_sub_u32 s19, s19, 1
	s_cmp_lg_u32 s19, 0
	s_cbranch_scc1 .Lwd_k_pq4
; #define MFMA32(a, b, c) __builtin_amdgcn_mfma_f32_32x32x16_bf16((a), (b), (c), 0, 0, 0)
;     ...
;   const u16* xg = X + (size_t)lr * RS + lc;
;   const u16* yg = Y + (size_t)lr * RS + lc;
;   u32x4 xr[4], yr[4];
; #pragma unroll
;   for (int it = 0; it < 4; ++it) {
;     xr[it] = *(const u32x4*)(xg + (size_t)it * 32 * RS);
;     yr[it] = *(const u32x4*)(yg + (size_t)it * 32 * RS);
;   }
;     ...
;   for (int kt = 0; kt < NKT; ++kt) {
;     __syncthreads();
; #pragma unroll
;     for (int it = 0; it < 4; ++it) {
;       *(u32x4*)(Xs + (lr + 32 * it) * LSTR + lc) = xr[it];
;       *(u32x4*)(Ys + (lr + 32 * it) * LSTR + lc) = yr[it];
;     }
;     __syncthreads();
;     if (kt + 1 < NKT) {
; #pragma unroll
;       for (int it = 0; it < 4; ++it) {
;         xr[it] = *(const u32x4*)(xg + (size_t)it * 32 * RS + (kt + 1) * 64);
;         yr[it] = *(const u32x4*)(yg + (size_t)it * 32 * RS + (kt + 1) * 64);
;       }
;     }
; #pragma unroll
;     for (int ks = 0; ks < 4; ++ks) {
;       bf16x8 af[TI], bfr[TJ];
; #pragma unroll
;       for (int a = 0; a < TI; ++a) af[a] = *(const bf16x8*)(Xs + (wi0 + a * 32 + fr) * LSTR + ks * 16 + fh);
; #pragma unroll
;       for (int b = 0; b < TJ; ++b) bfr[b] = *(const bf16x8*)(Ys + (wj0 + b * 32 + fr) * LSTR + ks * 16 + fh);
; #pragma unroll
;       for (int a = 0; a < TI; ++a)
; #pragma unroll
;         for (int b = 0; b < TJ; ++b) acc[a][b] = MFMA32(af[a], bfr[b], acc[a][b]);
;     }
;     __builtin_amdgcn_iglp_opt(1);
;   }
	v_xor_b32_e32 v133, 0x40, v118
	s_waitcnt vmcnt(11)
	ds_write_b128 v118, v[70:73] offset:16384
	s_waitcnt vmcnt(10)
	ds_write_b128 v133, v[78:81] offset:17408
	s_waitcnt vmcnt(9)
	ds_write_b128 v118, v[86:89] offset:18432
	s_waitcnt vmcnt(8)
	ds_write_b128 v133, v[94:97] offset:19456
	s_waitcnt vmcnt(4)
	s_waitcnt lgkmcnt(0)
	s_barrier
	s_add_u32 s100, s100, 0x80
	s_addc_u32 s101, s101, 0
	s_mov_b32 m0, s41
	s_nop 0
	global_load_lds_dwordx4 v120, s[100:101]
	global_load_lds_dwordx4 v121, s[100:101] offset:1024
	v_add_u32_e32 v133, 0x7800, v120
	global_load_lds_dwordx4 v133, s[100:101] offset:2048
	v_add_u32_e32 v133, 0x7800, v121
	global_load_lds_dwordx4 v133, s[100:101] offset:3072
	ds_read_b128 v[134:137], v114 offset:4096
	ds_read_b128 v[138:141], v114 offset:8192
	ds_read_b128 v[142:145], v114 offset:12288
	ds_read_b128 v[148:151], v114
	ds_read_b128 v[152:155], v115
	v_add_u32_e32 v0, s32, v114
	ds_read_b128 v[160:163], v0 offset:16384
	v_add_u32_e32 v0, s32, v115
	ds_read_b128 v[156:159], v0 offset:16384
	s_waitcnt lgkmcnt(1)
	v_mfma_f32_32x32x16_bf16 v[34:49], v[134:137], v[160:163], v[34:49]
	ds_read_b128 v[134:137], v115 offset:4096
	v_mfma_f32_32x32x16_bf16 v[18:33], v[138:141], v[160:163], v[18:33]
	ds_read_b128 v[138:141], v115 offset:8192
	v_mfma_f32_32x32x16_bf16 v[2:17], v[142:145], v[160:163], v[2:17]
	ds_read_b128 v[142:145], v115 offset:12288
	s_waitcnt lgkmcnt(2)
	v_mfma_f32_32x32x16_bf16 v[34:49], v[134:137], v[156:159], v[34:49]
	ds_read_b128 v[134:137], v116
	s_waitcnt lgkmcnt(2)
	v_mfma_f32_32x32x16_bf16 v[18:33], v[138:141], v[156:159], v[18:33]
	ds_read_b128 v[138:141], v116 offset:4096
	s_waitcnt lgkmcnt(2)
	v_mfma_f32_32x32x16_bf16 v[2:17], v[142:145], v[156:159], v[2:17]
	ds_read_b128 v[142:145], v116 offset:8192
	v_mfma_f32_32x32x16_bf16 v[50:65], v[148:151], v[160:163], v[50:65]
	ds_read_b128 v[148:151], v116 offset:12288
	v_mfma_f32_32x32x16_bf16 v[50:65], v[152:155], v[156:159], v[50:65]
	v_add_u32_e32 v0, s32, v116
	ds_read_b128 v[152:155], v0 offset:16384
	s_waitcnt lgkmcnt(0)
	v_mfma_f32_32x32x16_bf16 v[50:65], v[134:137], v[152:155], v[50:65]
	ds_read_b128 v[134:137], v117
	v_mfma_f32_32x32x16_bf16 v[34:49], v[138:141], v[152:155], v[34:49]
	ds_read_b128 v[138:141], v117 offset:4096
	v_mfma_f32_32x32x16_bf16 v[18:33], v[142:145], v[152:155], v[18:33]
	ds_read_b128 v[142:145], v117 offset:8192
	v_mfma_f32_32x32x16_bf16 v[2:17], v[148:151], v[152:155], v[2:17]
	ds_read_b128 v[148:151], v117 offset:12288
	v_add_u32_e32 v0, s32, v117
	ds_read_b128 v[152:155], v0 offset:16384
	s_waitcnt lgkmcnt(0)
	v_mfma_f32_32x32x16_bf16 v[50:65], v[134:137], v[152:155], v[50:65]
	v_mfma_f32_32x32x16_bf16 v[34:49], v[138:141], v[152:155], v[34:49]
	v_mfma_f32_32x32x16_bf16 v[18:33], v[142:145], v[152:155], v[18:33]
	v_mfma_f32_32x32x16_bf16 v[2:17], v[148:151], v[152:155], v[2:17]
	v_xor_b32_e32 v133, 0x40, v118
	s_waitcnt vmcnt(7)
	ds_write_b128 v118, v[66:69] offset:16384
	s_waitcnt vmcnt(6)
	ds_write_b128 v133, v[74:77] offset:17408
	s_waitcnt vmcnt(5)
	ds_write_b128 v118, v[82:85] offset:18432
	s_waitcnt vmcnt(4)
	ds_write_b128 v133, v[90:93] offset:19456
	s_waitcnt vmcnt(0)
	s_waitcnt lgkmcnt(0)
	s_barrier
	ds_read_b128 v[134:137], v114 offset:36864
	ds_read_b128 v[138:141], v114 offset:40992
	ds_read_b128 v[142:145], v114 offset:45088
	ds_read_b128 v[148:151], v114 offset:32768
	ds_read_b128 v[152:155], v115 offset:32768
	v_add_u32_e32 v0, s32, v114
	ds_read_b128 v[160:163], v0 offset:16384
	v_add_u32_e32 v0, s32, v115
	ds_read_b128 v[156:159], v0 offset:16384
	s_waitcnt lgkmcnt(1)
	v_mfma_f32_32x32x16_bf16 v[34:49], v[134:137], v[160:163], v[34:49]
	ds_read_b128 v[134:137], v115 offset:36864
	v_mfma_f32_32x32x16_bf16 v[18:33], v[138:141], v[160:163], v[18:33]
	ds_read_b128 v[138:141], v115 offset:40992
	v_mfma_f32_32x32x16_bf16 v[2:17], v[142:145], v[160:163], v[2:17]
	ds_read_b128 v[142:145], v115 offset:45088
	s_waitcnt lgkmcnt(2)
	v_mfma_f32_32x32x16_bf16 v[34:49], v[134:137], v[156:159], v[34:49]
	ds_read_b128 v[134:137], v116 offset:32768
	s_waitcnt lgkmcnt(2)
	v_mfma_f32_32x32x16_bf16 v[18:33], v[138:141], v[156:159], v[18:33]
	ds_read_b128 v[138:141], v116 offset:36864
	s_waitcnt lgkmcnt(2)
	v_mfma_f32_32x32x16_bf16 v[2:17], v[142:145], v[156:159], v[2:17]
	ds_read_b128 v[142:145], v116 offset:40992
	v_mfma_f32_32x32x16_bf16 v[50:65], v[148:151], v[160:163], v[50:65]
	ds_read_b128 v[148:151], v116 offset:45088
	v_mfma_f32_32x32x16_bf16 v[50:65], v[152:155], v[156:159], v[50:65]
	v_add_u32_e32 v0, s32, v116
	ds_read_b128 v[152:155], v0 offset:16384
	s_waitcnt lgkmcnt(0)
	v_mfma_f32_32x32x16_bf16 v[50:65], v[134:137], v[152:155], v[50:65]
	ds_read_b128 v[134:137], v117 offset:32768
	v_mfma_f32_32x32x16_bf16 v[34:49], v[138:141], v[152:155], v[34:49]
	ds_read_b128 v[138:141], v117 offset:36864
	v_mfma_f32_32x32x16_bf16 v[18:33], v[142:145], v[152:155], v[18:33]
	ds_read_b128 v[142:145], v117 offset:40992
	v_mfma_f32_32x32x16_bf16 v[2:17], v[148:151], v[152:155], v[2:17]
	ds_read_b128 v[148:151], v117 offset:45088
	v_add_u32_e32 v0, s32, v117
	ds_read_b128 v[152:155], v0 offset:16384
	s_waitcnt lgkmcnt(0)
	v_mfma_f32_32x32x16_bf16 v[50:65], v[134:137], v[152:155], v[50:65]
	v_mfma_f32_32x32x16_bf16 v[34:49], v[138:141], v[152:155], v[34:49]
	v_mfma_f32_32x32x16_bf16 v[18:33], v[142:145], v[152:155], v[18:33]
	v_mfma_f32_32x32x16_bf16 v[2:17], v[148:151], v[152:155], v[2:17]
	s_cmp_lg_u64 s[46:47], 0
	s_cbranch_scc1 .Lpq_nopf
	s_add_u32 s100, s100, 0x3f880
	s_addc_u32 s101, s101, 0
	global_load_dwordx4 v[70:73], v119, s[44:45]
	v_add_u32_e32 v133, 0x4000, v119
	global_load_dwordx4 v[78:81], v133, s[44:45]
	v_add_u32_e32 v133, 0x8000, v119
	global_load_dwordx4 v[86:89], v133, s[44:45]
	v_add_u32_e32 v133, 0xc000, v119
	global_load_dwordx4 v[94:97], v133, s[44:45]
	s_mov_b32 m0, s32
	s_nop 0
	global_load_lds_dwordx4 v120, s[100:101]
	global_load_lds_dwordx4 v121, s[100:101] offset:1024
	v_add_u32_e32 v133, 0x7800, v120
	global_load_lds_dwordx4 v133, s[100:101] offset:2048
	v_add_u32_e32 v133, 0x7800, v121
	global_load_lds_dwordx4 v133, s[100:101] offset:3072
	global_load_dwordx4 v[66:69], v119, s[44:45] offset:128
	v_add_u32_e32 v133, 0x4000, v119
	global_load_dwordx4 v[74:77], v133, s[44:45] offset:128
	v_add_u32_e32 v133, 0x8000, v119
	global_load_dwordx4 v[82:85], v133, s[44:45] offset:128
	v_add_u32_e32 v133, 0xc000, v119
	global_load_dwordx4 v[90:93], v133, s[44:45] offset:128
; DI void phase_peer_q(const Params& p, int layer, u16* lds, const int WAVE_S) {
;     ...
; #pragma unroll
;       for (int i = 0; i < 16; ++i) t[i] = -3.0e38f;
; #pragma unroll
;       for (int nt = 0; nt < 4; ++nt)
; #pragma unroll
;         for (int i = 0; i < 16; ++i) {
;           const uint32_t n = nt * 32 + (i & 3) + 8 * (i >> 2) + 4 * h;
;           const float v = __uint_as_float((__float_as_uint(acc[nt][0][i]) & ~127u) | n);
;           ins16n(t, v, nt * 16 + i);
;         }
.Lpq_nopf:
	s_nop 7
	s_nop 7
	s_andn2_b64 vcc, exec, s[48:49]
	v_and_or_b32 v0, v50, s88, v123
	v_max_f32_e32 v0, v0, v0
	v_or_b32_e32 v50, 1, v123
	v_max_f32_e32 v0, 0xff61b1e6, v0
	v_and_or_b32 v50, v51, s88, v50
	v_med3_f32 v51, v0, v50, s92
	v_max_f32_e32 v50, v50, v50
	v_max_f32_e32 v0, v0, v50
	v_or_b32_e32 v50, 2, v123
	v_and_or_b32 v50, v52, s88, v50
	v_med3_f32 v52, v51, v50, s92
	v_med3_f32 v51, v0, v51, v50
	v_max_f32_e32 v50, v50, v50
	v_max_f32_e32 v0, v0, v50
	v_or_b32_e32 v50, 3, v123
	v_and_or_b32 v50, v53, s88, v50
	v_med3_f32 v53, v52, v50, s92
	v_med3_f32 v52, v51, v52, v50
	v_med3_f32 v51, v0, v51, v50
	v_max_f32_e32 v50, v50, v50
	v_max_f32_e32 v0, v0, v50
	v_or_b32_e32 v50, 8, v123
	v_and_or_b32 v50, v54, s88, v50
	v_med3_f32 v54, v53, v50, s92
	v_med3_f32 v53, v52, v53, v50
	v_med3_f32 v52, v51, v52, v50
	v_med3_f32 v51, v0, v51, v50
	v_max_f32_e32 v50, v50, v50
	v_max_f32_e32 v0, v0, v50
	v_or_b32_e32 v50, 9, v123
	v_and_or_b32 v50, v55, s88, v50
	v_med3_f32 v55, v54, v50, s92
	v_med3_f32 v54, v53, v54, v50
	v_med3_f32 v53, v52, v53, v50
	v_med3_f32 v52, v51, v52, v50
	v_med3_f32 v51, v0, v51, v50
	v_max_f32_e32 v50, v50, v50
	v_max_f32_e32 v0, v0, v50
	v_or_b32_e32 v50, 10, v123
	v_and_or_b32 v50, v56, s88, v50
	v_med3_f32 v56, v55, v50, s92
	v_med3_f32 v55, v54, v55, v50
	v_med3_f32 v54, v53, v54, v50
	v_med3_f32 v53, v52, v53, v50
	v_med3_f32 v52, v51, v52, v50
	v_med3_f32 v51, v0, v51, v50
	v_max_f32_e32 v50, v50, v50
	v_max_f32_e32 v0, v0, v50
	v_or_b32_e32 v50, 11, v123
	v_and_or_b32 v50, v57, s88, v50
	v_med3_f32 v57, v56, v50, s92
	v_med3_f32 v56, v55, v56, v50
	v_med3_f32 v55, v54, v55, v50
	v_med3_f32 v54, v53, v54, v50
	v_med3_f32 v53, v52, v53, v50
	v_med3_f32 v52, v51, v52, v50
	v_med3_f32 v51, v0, v51, v50
	v_max_f32_e32 v50, v50, v50
	v_max_f32_e32 v0, v0, v50
	v_or_b32_e32 v50, 16, v123
	v_and_or_b32 v50, v58, s88, v50
	v_med3_f32 v58, v57, v50, s92
	v_med3_f32 v57, v56, v57, v50
	v_med3_f32 v56, v55, v56, v50
	v_med3_f32 v55, v54, v55, v50
	v_med3_f32 v54, v53, v54, v50
	v_med3_f32 v53, v52, v53, v50
	v_med3_f32 v52, v51, v52, v50
	v_med3_f32 v51, v0, v51, v50
	v_max_f32_e32 v50, v50, v50
	v_max_f32_e32 v0, v0, v50
	v_or_b32_e32 v50, 17, v123
	v_and_or_b32 v50, v59, s88, v50
	v_med3_f32 v59, v58, v50, s92
	v_med3_f32 v58, v57, v58, v50
	v_med3_f32 v57, v56, v57, v50
	v_med3_f32 v56, v55, v56, v50
	v_med3_f32 v55, v54, v55, v50
	v_med3_f32 v54, v53, v54, v50
	v_med3_f32 v53, v52, v53, v50
	v_med3_f32 v52, v51, v52, v50
	v_med3_f32 v51, v0, v51, v50
	v_max_f32_e32 v50, v50, v50
	v_max_f32_e32 v0, v0, v50
	v_or_b32_e32 v50, 18, v123
	v_and_or_b32 v50, v60, s88, v50
	v_med3_f32 v60, v59, v50, s92
	v_med3_f32 v59, v58, v59, v50
	v_med3_f32 v58, v57, v58, v50
	v_med3_f32 v57, v56, v57, v50
	v_med3_f32 v56, v55, v56, v50
	v_med3_f32 v55, v54, v55, v50
	v_med3_f32 v54, v53, v54, v50
	v_med3_f32 v53, v52, v53, v50
	v_med3_f32 v52, v51, v52, v50
	v_med3_f32 v51, v0, v51, v50
	v_max_f32_e32 v50, v50, v50
	v_max_f32_e32 v0, v0, v50
	v_or_b32_e32 v50, 19, v123
	v_and_or_b32 v50, v61, s88, v50
	v_med3_f32 v61, v60, v50, s92
	v_med3_f32 v60, v59, v60, v50
	v_med3_f32 v59, v58, v59, v50
	v_med3_f32 v58, v57, v58, v50
	v_med3_f32 v57, v56, v57, v50
	v_med3_f32 v56, v55, v56, v50
	v_med3_f32 v55, v54, v55, v50
	v_med3_f32 v54, v53, v54, v50
	v_med3_f32 v53, v52, v53, v50
	v_med3_f32 v52, v51, v52, v50
	v_med3_f32 v51, v0, v51, v50
	v_max_f32_e32 v50, v50, v50
	v_max_f32_e32 v0, v0, v50
	v_or_b32_e32 v50, 24, v123
	v_and_or_b32 v50, v62, s88, v50
	v_med3_f32 v62, v61, v50, s92
	v_med3_f32 v61, v60, v61, v50
	v_med3_f32 v60, v59, v60, v50
	v_med3_f32 v59, v58, v59, v50
	v_med3_f32 v58, v57, v58, v50
	v_med3_f32 v57, v56, v57, v50
	v_med3_f32 v56, v55, v56, v50
	v_med3_f32 v55, v54, v55, v50
	v_med3_f32 v54, v53, v54, v50
	v_med3_f32 v53, v52, v53, v50
	v_med3_f32 v52, v51, v52, v50
	v_med3_f32 v51, v0, v51, v50
	v_max_f32_e32 v50, v50, v50
	v_max_f32_e32 v0, v0, v50
	v_or_b32_e32 v50, 25, v123
	v_and_or_b32 v50, v63, s88, v50
	v_med3_f32 v63, v62, v50, s92
	v_med3_f32 v62, v61, v62, v50
	v_med3_f32 v61, v60, v61, v50
	v_med3_f32 v60, v59, v60, v50
	v_med3_f32 v59, v58, v59, v50
	v_med3_f32 v58, v57, v58, v50
	v_med3_f32 v57, v56, v57, v50
	v_med3_f32 v56, v55, v56, v50
	v_med3_f32 v55, v54, v55, v50
	v_med3_f32 v54, v53, v54, v50
	v_med3_f32 v53, v52, v53, v50
	v_med3_f32 v52, v51, v52, v50
	v_med3_f32 v51, v0, v51, v50
	v_max_f32_e32 v50, v50, v50
	v_max_f32_e32 v0, v0, v50
	v_or_b32_e32 v50, 26, v123
	v_and_or_b32 v50, v64, s88, v50
	v_med3_f32 v64, v63, v50, s92
	v_med3_f32 v63, v62, v63, v50
	v_med3_f32 v62, v61, v62, v50
	v_med3_f32 v61, v60, v61, v50
	v_med3_f32 v60, v59, v60, v50
	v_med3_f32 v59, v58, v59, v50
	v_med3_f32 v58, v57, v58, v50
	v_med3_f32 v57, v56, v57, v50
	v_med3_f32 v56, v55, v56, v50
	v_med3_f32 v55, v54, v55, v50
	v_med3_f32 v54, v53, v54, v50
	v_med3_f32 v53, v52, v53, v50
	v_med3_f32 v52, v51, v52, v50
	v_med3_f32 v51, v0, v51, v50
	v_max_f32_e32 v50, v50, v50
	v_max_f32_e32 v0, v0, v50
	v_or_b32_e32 v50, 27, v123
	v_and_or_b32 v50, v65, s88, v50
	v_med3_f32 v65, v64, v50, s92
	v_med3_f32 v64, v63, v64, v50
	v_med3_f32 v63, v62, v63, v50
	v_med3_f32 v62, v61, v62, v50
	v_med3_f32 v61, v60, v61, v50
	v_med3_f32 v60, v59, v60, v50
	v_med3_f32 v59, v58, v59, v50
	v_med3_f32 v58, v57, v58, v50
	v_med3_f32 v57, v56, v57, v50
	v_med3_f32 v56, v55, v56, v50
	v_med3_f32 v55, v54, v55, v50
	v_med3_f32 v54, v53, v54, v50
	v_med3_f32 v53, v52, v53, v50
	v_med3_f32 v52, v51, v52, v50
	v_med3_f32 v51, v0, v51, v50
	v_max_f32_e32 v50, v50, v50
	v_max_f32_e32 v0, v0, v50
	v_or_b32_e32 v50, 32, v123
; DI void phase_peer_q(const Params& p, int layer, u16* lds, const int WAVE_S) {
;     ...
; #pragma unroll
;       for (int nt = 0; nt < 4; ++nt)
; #pragma unroll
;         for (int i = 0; i < 16; ++i) {
;           const uint32_t n = nt * 32 + (i & 3) + 8 * (i >> 2) + 4 * h;
;           const float v = __uint_as_float((__float_as_uint(acc[nt][0][i]) & ~127u) | n);
;           ins16n(t, v, nt * 16 + i);
;         }
	v_and_or_b32 v34, v34, s88, v50
	v_med3_f32 v50, v64, v65, v34
	v_med3_f32 v64, v63, v64, v34
	v_med3_f32 v63, v62, v63, v34
	v_med3_f32 v62, v61, v62, v34
	v_med3_f32 v61, v60, v61, v34
	v_med3_f32 v60, v59, v60, v34
	v_med3_f32 v59, v58, v59, v34
	v_med3_f32 v58, v57, v58, v34
	v_med3_f32 v57, v56, v57, v34
	v_med3_f32 v56, v55, v56, v34
	v_med3_f32 v55, v54, v55, v34
	v_med3_f32 v54, v53, v54, v34
	v_med3_f32 v53, v52, v53, v34
	v_med3_f32 v52, v51, v52, v34
	v_med3_f32 v51, v0, v51, v34
	v_max_f32_e32 v34, v34, v34
	v_max_f32_e32 v0, v0, v34
	v_or_b32_e32 v34, 33, v123
	v_and_or_b32 v34, v35, s88, v34
	v_med3_f32 v35, v64, v50, v34
	v_med3_f32 v50, v63, v64, v34
	v_med3_f32 v63, v62, v63, v34
	v_med3_f32 v62, v61, v62, v34
	v_med3_f32 v61, v60, v61, v34
	v_med3_f32 v60, v59, v60, v34
	v_med3_f32 v59, v58, v59, v34
	v_med3_f32 v58, v57, v58, v34
	v_med3_f32 v57, v56, v57, v34
	v_med3_f32 v56, v55, v56, v34
	v_med3_f32 v55, v54, v55, v34
	v_med3_f32 v54, v53, v54, v34
	v_med3_f32 v53, v52, v53, v34
	v_med3_f32 v52, v51, v52, v34
	v_med3_f32 v51, v0, v51, v34
	v_max_f32_e32 v34, v34, v34
	v_max_f32_e32 v0, v0, v34
	v_or_b32_e32 v34, 34, v123
	v_and_or_b32 v34, v36, s88, v34
	v_med3_f32 v35, v50, v35, v34
	v_med3_f32 v36, v63, v50, v34
	v_med3_f32 v50, v62, v63, v34
	v_med3_f32 v62, v61, v62, v34
	v_med3_f32 v61, v60, v61, v34
	v_med3_f32 v60, v59, v60, v34
	v_med3_f32 v59, v58, v59, v34
	v_med3_f32 v58, v57, v58, v34
	v_med3_f32 v57, v56, v57, v34
	v_med3_f32 v56, v55, v56, v34
	v_med3_f32 v55, v54, v55, v34
	v_med3_f32 v54, v53, v54, v34
	v_med3_f32 v53, v52, v53, v34
	v_med3_f32 v52, v51, v52, v34
	v_med3_f32 v51, v0, v51, v34
	v_max_f32_e32 v34, v34, v34
	v_max_f32_e32 v0, v0, v34
	v_or_b32_e32 v34, 35, v123
	v_and_or_b32 v34, v37, s88, v34
	v_med3_f32 v35, v36, v35, v34
	v_med3_f32 v36, v50, v36, v34
	v_med3_f32 v37, v62, v50, v34
	v_med3_f32 v50, v61, v62, v34
	v_med3_f32 v61, v60, v61, v34
	v_med3_f32 v60, v59, v60, v34
	v_med3_f32 v59, v58, v59, v34
	v_med3_f32 v58, v57, v58, v34
	v_med3_f32 v57, v56, v57, v34
	v_med3_f32 v56, v55, v56, v34
	v_med3_f32 v55, v54, v55, v34
	v_med3_f32 v54, v53, v54, v34
	v_med3_f32 v53, v52, v53, v34
	v_med3_f32 v52, v51, v52, v34
	v_med3_f32 v51, v0, v51, v34
	v_max_f32_e32 v34, v34, v34
	v_max_f32_e32 v0, v0, v34
	v_or_b32_e32 v34, 40, v123
	v_and_or_b32 v34, v38, s88, v34
	v_med3_f32 v35, v36, v35, v34
	v_med3_f32 v36, v37, v36, v34
	v_med3_f32 v37, v50, v37, v34
	v_med3_f32 v38, v61, v50, v34
	v_med3_f32 v50, v60, v61, v34
	v_med3_f32 v60, v59, v60, v34
	v_med3_f32 v59, v58, v59, v34
	v_med3_f32 v58, v57, v58, v34
	v_med3_f32 v57, v56, v57, v34
	v_med3_f32 v56, v55, v56, v34
	v_med3_f32 v55, v54, v55, v34
	v_med3_f32 v54, v53, v54, v34
	v_med3_f32 v53, v52, v53, v34
	v_med3_f32 v52, v51, v52, v34
	v_med3_f32 v51, v0, v51, v34
	v_max_f32_e32 v34, v34, v34
	v_max_f32_e32 v0, v0, v34
	v_or_b32_e32 v34, 41, v123
	v_and_or_b32 v34, v39, s88, v34
	v_med3_f32 v35, v36, v35, v34
	v_med3_f32 v36, v37, v36, v34
	v_med3_f32 v37, v38, v37, v34
	v_med3_f32 v38, v50, v38, v34
	v_med3_f32 v39, v60, v50, v34
	v_med3_f32 v50, v59, v60, v34
	v_med3_f32 v59, v58, v59, v34
	v_med3_f32 v58, v57, v58, v34
	v_med3_f32 v57, v56, v57, v34
	v_med3_f32 v56, v55, v56, v34
	v_med3_f32 v55, v54, v55, v34
	v_med3_f32 v54, v53, v54, v34
	v_med3_f32 v53, v52, v53, v34
	v_med3_f32 v52, v51, v52, v34
	v_med3_f32 v51, v0, v51, v34
	v_max_f32_e32 v34, v34, v34
	v_max_f32_e32 v0, v0, v34
	v_or_b32_e32 v34, 42, v123
	v_and_or_b32 v34, v40, s88, v34
	v_med3_f32 v35, v36, v35, v34
	v_med3_f32 v36, v37, v36, v34
	v_med3_f32 v37, v38, v37, v34
	v_med3_f32 v38, v39, v38, v34
	v_med3_f32 v39, v50, v39, v34
	v_med3_f32 v40, v59, v50, v34
	v_med3_f32 v50, v58, v59, v34
	v_med3_f32 v58, v57, v58, v34
	v_med3_f32 v57, v56, v57, v34
	v_med3_f32 v56, v55, v56, v34
	v_med3_f32 v55, v54, v55, v34
	v_med3_f32 v54, v53, v54, v34
	v_med3_f32 v53, v52, v53, v34
	v_med3_f32 v52, v51, v52, v34
	v_med3_f32 v51, v0, v51, v34
	v_max_f32_e32 v34, v34, v34
	v_max_f32_e32 v0, v0, v34
	v_or_b32_e32 v34, 43, v123
	v_and_or_b32 v34, v41, s88, v34
	v_med3_f32 v35, v36, v35, v34
	v_med3_f32 v36, v37, v36, v34
	v_med3_f32 v37, v38, v37, v34
	v_med3_f32 v38, v39, v38, v34
	v_med3_f32 v39, v40, v39, v34
	v_med3_f32 v40, v50, v40, v34
	v_med3_f32 v41, v58, v50, v34
	v_med3_f32 v50, v57, v58, v34
	v_med3_f32 v57, v56, v57, v34
	v_med3_f32 v56, v55, v56, v34
	v_med3_f32 v55, v54, v55, v34
	v_med3_f32 v54, v53, v54, v34
	v_med3_f32 v53, v52, v53, v34
	v_med3_f32 v52, v51, v52, v34
	v_med3_f32 v51, v0, v51, v34
	v_max_f32_e32 v34, v34, v34
	v_max_f32_e32 v0, v0, v34
	v_or_b32_e32 v34, 48, v123
	v_and_or_b32 v34, v42, s88, v34
	v_med3_f32 v35, v36, v35, v34
	v_med3_f32 v36, v37, v36, v34
	v_med3_f32 v37, v38, v37, v34
	v_med3_f32 v38, v39, v38, v34
	v_med3_f32 v39, v40, v39, v34
	v_med3_f32 v40, v41, v40, v34
	v_med3_f32 v41, v50, v41, v34
	v_med3_f32 v42, v57, v50, v34
	v_med3_f32 v50, v56, v57, v34
	v_med3_f32 v56, v55, v56, v34
	v_med3_f32 v55, v54, v55, v34
	v_med3_f32 v54, v53, v54, v34
	v_med3_f32 v53, v52, v53, v34
	v_med3_f32 v52, v51, v52, v34
	v_med3_f32 v51, v0, v51, v34
	v_max_f32_e32 v34, v34, v34
	v_max_f32_e32 v0, v0, v34
	v_or_b32_e32 v34, 49, v123
	v_and_or_b32 v34, v43, s88, v34
	v_med3_f32 v35, v36, v35, v34
	v_med3_f32 v36, v37, v36, v34
	v_med3_f32 v37, v38, v37, v34
	v_med3_f32 v38, v39, v38, v34
	v_med3_f32 v39, v40, v39, v34
	v_med3_f32 v40, v41, v40, v34
	v_med3_f32 v41, v42, v41, v34
	v_med3_f32 v42, v50, v42, v34
	v_med3_f32 v43, v56, v50, v34
	v_med3_f32 v50, v55, v56, v34
	v_med3_f32 v55, v54, v55, v34
	v_med3_f32 v54, v53, v54, v34
; DI void phase_peer_q(const Params& p, int layer, u16* lds, const int WAVE_S) {
;     ...
; #pragma unroll
;       for (int nt = 0; nt < 4; ++nt)
; #pragma unroll
;         for (int i = 0; i < 16; ++i) {
;           const uint32_t n = nt * 32 + (i & 3) + 8 * (i >> 2) + 4 * h;
;           const float v = __uint_as_float((__float_as_uint(acc[nt][0][i]) & ~127u) | n);
;           ins16n(t, v, nt * 16 + i);
;         }
	v_med3_f32 v53, v52, v53, v34
	v_med3_f32 v52, v51, v52, v34
	v_med3_f32 v51, v0, v51, v34
	v_max_f32_e32 v34, v34, v34
	v_max_f32_e32 v0, v0, v34
	v_or_b32_e32 v34, 50, v123
	v_and_or_b32 v34, v44, s88, v34
	v_med3_f32 v35, v36, v35, v34
	v_med3_f32 v36, v37, v36, v34
	v_med3_f32 v37, v38, v37, v34
	v_med3_f32 v38, v39, v38, v34
	v_med3_f32 v39, v40, v39, v34
	v_med3_f32 v40, v41, v40, v34
	v_med3_f32 v41, v42, v41, v34
	v_med3_f32 v42, v43, v42, v34
	v_med3_f32 v43, v50, v43, v34
	v_med3_f32 v44, v55, v50, v34
	v_med3_f32 v50, v54, v55, v34
	v_med3_f32 v54, v53, v54, v34
	v_med3_f32 v53, v52, v53, v34
	v_med3_f32 v52, v51, v52, v34
	v_med3_f32 v51, v0, v51, v34
	v_max_f32_e32 v34, v34, v34
	v_max_f32_e32 v0, v0, v34
	v_or_b32_e32 v34, 51, v123
	v_and_or_b32 v34, v45, s88, v34
	v_med3_f32 v35, v36, v35, v34
	v_med3_f32 v36, v37, v36, v34
	v_med3_f32 v37, v38, v37, v34
	v_med3_f32 v38, v39, v38, v34
	v_med3_f32 v39, v40, v39, v34
	v_med3_f32 v40, v41, v40, v34
	v_med3_f32 v41, v42, v41, v34
	v_med3_f32 v42, v43, v42, v34
	v_med3_f32 v43, v44, v43, v34
	v_med3_f32 v44, v50, v44, v34
	v_med3_f32 v45, v54, v50, v34
	v_med3_f32 v50, v53, v54, v34
	v_med3_f32 v53, v52, v53, v34
	v_med3_f32 v52, v51, v52, v34
	v_med3_f32 v51, v0, v51, v34
	v_max_f32_e32 v34, v34, v34
	v_max_f32_e32 v0, v0, v34
	v_or_b32_e32 v34, 56, v123
	v_and_or_b32 v34, v46, s88, v34
	v_med3_f32 v35, v36, v35, v34
	v_med3_f32 v36, v37, v36, v34
	v_med3_f32 v37, v38, v37, v34
	v_med3_f32 v38, v39, v38, v34
	v_med3_f32 v39, v40, v39, v34
	v_med3_f32 v40, v41, v40, v34
	v_med3_f32 v41, v42, v41, v34
	v_med3_f32 v42, v43, v42, v34
	v_med3_f32 v43, v44, v43, v34
	v_med3_f32 v44, v45, v44, v34
	v_med3_f32 v45, v50, v45, v34
	v_med3_f32 v46, v53, v50, v34
	v_med3_f32 v50, v52, v53, v34
	v_med3_f32 v52, v51, v52, v34
	v_med3_f32 v51, v0, v51, v34
	v_max_f32_e32 v34, v34, v34
	v_max_f32_e32 v0, v0, v34
	v_or_b32_e32 v34, 57, v123
	v_and_or_b32 v34, v47, s88, v34
	v_med3_f32 v35, v36, v35, v34
	v_med3_f32 v36, v37, v36, v34
	v_med3_f32 v37, v38, v37, v34
	v_med3_f32 v38, v39, v38, v34
	v_med3_f32 v39, v40, v39, v34
	v_med3_f32 v40, v41, v40, v34
	v_med3_f32 v41, v42, v41, v34
	v_med3_f32 v42, v43, v42, v34
	v_med3_f32 v43, v44, v43, v34
	v_med3_f32 v44, v45, v44, v34
	v_med3_f32 v45, v46, v45, v34
	v_med3_f32 v46, v50, v46, v34
	v_med3_f32 v47, v52, v50, v34
	v_med3_f32 v50, v51, v52, v34
	v_med3_f32 v51, v0, v51, v34
	v_max_f32_e32 v34, v34, v34
	v_max_f32_e32 v0, v0, v34
	v_or_b32_e32 v34, 58, v123
	v_and_or_b32 v34, v48, s88, v34
	v_med3_f32 v35, v36, v35, v34
	v_med3_f32 v36, v37, v36, v34
	v_med3_f32 v37, v38, v37, v34
	v_med3_f32 v38, v39, v38, v34
	v_med3_f32 v39, v40, v39, v34
	v_med3_f32 v40, v41, v40, v34
	v_med3_f32 v41, v42, v41, v34
	v_med3_f32 v42, v43, v42, v34
	v_med3_f32 v43, v44, v43, v34
	v_med3_f32 v44, v45, v44, v34
	v_med3_f32 v45, v46, v45, v34
	v_med3_f32 v46, v47, v46, v34
	v_med3_f32 v47, v50, v47, v34
	v_med3_f32 v48, v51, v50, v34
	v_med3_f32 v50, v0, v51, v34
	v_max_f32_e32 v34, v34, v34
	v_max_f32_e32 v0, v0, v34
	v_or_b32_e32 v34, 59, v123
	v_and_or_b32 v34, v49, s88, v34
	v_med3_f32 v35, v36, v35, v34
	v_med3_f32 v36, v37, v36, v34
	v_med3_f32 v37, v38, v37, v34
	v_med3_f32 v38, v39, v38, v34
	v_med3_f32 v39, v40, v39, v34
	v_med3_f32 v40, v41, v40, v34
	v_med3_f32 v41, v42, v41, v34
	v_med3_f32 v42, v43, v42, v34
	v_med3_f32 v43, v44, v43, v34
	v_med3_f32 v44, v45, v44, v34
	v_med3_f32 v45, v46, v45, v34
	v_med3_f32 v46, v47, v46, v34
	v_med3_f32 v47, v48, v47, v34
	v_med3_f32 v48, v50, v48, v34
	v_med3_f32 v49, v0, v50, v34
	v_max_f32_e32 v34, v34, v34
	v_max_f32_e32 v0, v0, v34
	v_or_b32_e32 v34, 64, v123
	v_and_or_b32 v18, v18, s88, v34
	v_med3_f32 v34, v36, v35, v18
	v_med3_f32 v35, v37, v36, v18
	v_med3_f32 v36, v38, v37, v18
	v_med3_f32 v37, v39, v38, v18
	v_med3_f32 v38, v40, v39, v18
	v_med3_f32 v39, v41, v40, v18
	v_med3_f32 v40, v42, v41, v18
	v_med3_f32 v41, v43, v42, v18
	v_med3_f32 v42, v44, v43, v18
	v_med3_f32 v43, v45, v44, v18
	v_med3_f32 v44, v46, v45, v18
	v_med3_f32 v45, v47, v46, v18
	v_med3_f32 v46, v48, v47, v18
	v_med3_f32 v47, v49, v48, v18
	v_med3_f32 v48, v0, v49, v18
	v_max_f32_e32 v18, v18, v18
	v_max_f32_e32 v0, v0, v18
	v_or_b32_e32 v18, 0x41, v123
	v_and_or_b32 v18, v19, s88, v18
	v_med3_f32 v19, v35, v34, v18
	v_med3_f32 v34, v36, v35, v18
	v_med3_f32 v35, v37, v36, v18
	v_med3_f32 v36, v38, v37, v18
	v_med3_f32 v37, v39, v38, v18
	v_med3_f32 v38, v40, v39, v18
	v_med3_f32 v39, v41, v40, v18
	v_med3_f32 v40, v42, v41, v18
	v_med3_f32 v41, v43, v42, v18
	v_med3_f32 v42, v44, v43, v18
	v_med3_f32 v43, v45, v44, v18
	v_med3_f32 v44, v46, v45, v18
	v_med3_f32 v45, v47, v46, v18
	v_med3_f32 v46, v48, v47, v18
	v_med3_f32 v47, v0, v48, v18
	v_max_f32_e32 v18, v18, v18
	v_max_f32_e32 v0, v0, v18
	v_or_b32_e32 v18, 0x42, v123
	v_and_or_b32 v18, v20, s88, v18
	v_med3_f32 v19, v34, v19, v18
	v_med3_f32 v20, v35, v34, v18
	v_med3_f32 v34, v36, v35, v18
	v_med3_f32 v35, v37, v36, v18
	v_med3_f32 v36, v38, v37, v18
	v_med3_f32 v37, v39, v38, v18
	v_med3_f32 v38, v40, v39, v18
	v_med3_f32 v39, v41, v40, v18
	v_med3_f32 v40, v42, v41, v18
	v_med3_f32 v41, v43, v42, v18
	v_med3_f32 v42, v44, v43, v18
	v_med3_f32 v43, v45, v44, v18
	v_med3_f32 v44, v46, v45, v18
	v_med3_f32 v45, v47, v46, v18
	v_med3_f32 v46, v0, v47, v18
	v_max_f32_e32 v18, v18, v18
	v_max_f32_e32 v0, v0, v18
	v_or_b32_e32 v18, 0x43, v123
	v_and_or_b32 v18, v21, s88, v18
	v_med3_f32 v19, v20, v19, v18
	v_med3_f32 v20, v34, v20, v18
	v_med3_f32 v21, v35, v34, v18
	v_med3_f32 v34, v36, v35, v18
	v_med3_f32 v35, v37, v36, v18
	v_med3_f32 v36, v38, v37, v18
; DI void phase_peer_q(const Params& p, int layer, u16* lds, const int WAVE_S) {
;     ...
; #pragma unroll
;       for (int nt = 0; nt < 4; ++nt)
; #pragma unroll
;         for (int i = 0; i < 16; ++i) {
;           const uint32_t n = nt * 32 + (i & 3) + 8 * (i >> 2) + 4 * h;
;           const float v = __uint_as_float((__float_as_uint(acc[nt][0][i]) & ~127u) | n);
;           ins16n(t, v, nt * 16 + i);
;         }
	v_med3_f32 v37, v39, v38, v18
	v_med3_f32 v38, v40, v39, v18
	v_med3_f32 v39, v41, v40, v18
	v_med3_f32 v40, v42, v41, v18
	v_med3_f32 v41, v43, v42, v18
	v_med3_f32 v42, v44, v43, v18
	v_med3_f32 v43, v45, v44, v18
	v_med3_f32 v44, v46, v45, v18
	v_med3_f32 v45, v0, v46, v18
	v_max_f32_e32 v18, v18, v18
	v_max_f32_e32 v0, v0, v18
	v_or_b32_e32 v18, 0x48, v123
	v_and_or_b32 v18, v22, s88, v18
	v_med3_f32 v19, v20, v19, v18
	v_med3_f32 v20, v21, v20, v18
	v_med3_f32 v21, v34, v21, v18
	v_med3_f32 v22, v35, v34, v18
	v_med3_f32 v34, v36, v35, v18
	v_med3_f32 v35, v37, v36, v18
	v_med3_f32 v36, v38, v37, v18
	v_med3_f32 v37, v39, v38, v18
	v_med3_f32 v38, v40, v39, v18
	v_med3_f32 v39, v41, v40, v18
	v_med3_f32 v40, v42, v41, v18
	v_med3_f32 v41, v43, v42, v18
	v_med3_f32 v42, v44, v43, v18
	v_med3_f32 v43, v45, v44, v18
	v_med3_f32 v44, v0, v45, v18
	v_max_f32_e32 v18, v18, v18
	v_max_f32_e32 v0, v0, v18
	v_or_b32_e32 v18, 0x49, v123
	v_and_or_b32 v18, v23, s88, v18
	v_med3_f32 v19, v20, v19, v18
	v_med3_f32 v20, v21, v20, v18
	v_med3_f32 v21, v22, v21, v18
	v_med3_f32 v22, v34, v22, v18
	v_med3_f32 v23, v35, v34, v18
	v_med3_f32 v34, v36, v35, v18
	v_med3_f32 v35, v37, v36, v18
	v_med3_f32 v36, v38, v37, v18
	v_med3_f32 v37, v39, v38, v18
	v_med3_f32 v38, v40, v39, v18
	v_med3_f32 v39, v41, v40, v18
	v_med3_f32 v40, v42, v41, v18
	v_med3_f32 v41, v43, v42, v18
	v_med3_f32 v42, v44, v43, v18
	v_med3_f32 v43, v0, v44, v18
	v_max_f32_e32 v18, v18, v18
	v_max_f32_e32 v0, v0, v18
	v_or_b32_e32 v18, 0x4a, v123
	v_and_or_b32 v18, v24, s88, v18
	v_med3_f32 v19, v20, v19, v18
	v_med3_f32 v20, v21, v20, v18
	v_med3_f32 v21, v22, v21, v18
	v_med3_f32 v22, v23, v22, v18
	v_med3_f32 v23, v34, v23, v18
	v_med3_f32 v24, v35, v34, v18
	v_med3_f32 v34, v36, v35, v18
	v_med3_f32 v35, v37, v36, v18
	v_med3_f32 v36, v38, v37, v18
	v_med3_f32 v37, v39, v38, v18
	v_med3_f32 v38, v40, v39, v18
	v_med3_f32 v39, v41, v40, v18
	v_med3_f32 v40, v42, v41, v18
	v_med3_f32 v41, v43, v42, v18
	v_med3_f32 v42, v0, v43, v18
	v_max_f32_e32 v18, v18, v18
	v_max_f32_e32 v0, v0, v18
	v_or_b32_e32 v18, 0x4b, v123
	v_and_or_b32 v18, v25, s88, v18
	v_med3_f32 v19, v20, v19, v18
	v_med3_f32 v20, v21, v20, v18
	v_med3_f32 v21, v22, v21, v18
	v_med3_f32 v22, v23, v22, v18
	v_med3_f32 v23, v24, v23, v18
	v_med3_f32 v24, v34, v24, v18
	v_med3_f32 v25, v35, v34, v18
	v_med3_f32 v34, v36, v35, v18
	v_med3_f32 v35, v37, v36, v18
	v_med3_f32 v36, v38, v37, v18
	v_med3_f32 v37, v39, v38, v18
	v_med3_f32 v38, v40, v39, v18
	v_med3_f32 v39, v41, v40, v18
	v_med3_f32 v40, v42, v41, v18
	v_med3_f32 v41, v0, v42, v18
	v_max_f32_e32 v18, v18, v18
	v_max_f32_e32 v0, v0, v18
	v_or_b32_e32 v18, 0x50, v123
	v_and_or_b32 v18, v26, s88, v18
	v_med3_f32 v19, v20, v19, v18
	v_med3_f32 v20, v21, v20, v18
	v_med3_f32 v21, v22, v21, v18
	v_med3_f32 v22, v23, v22, v18
	v_med3_f32 v23, v24, v23, v18
	v_med3_f32 v24, v25, v24, v18
	v_med3_f32 v25, v34, v25, v18
	v_med3_f32 v26, v35, v34, v18
	v_med3_f32 v34, v36, v35, v18
	v_med3_f32 v35, v37, v36, v18
	v_med3_f32 v36, v38, v37, v18
	v_med3_f32 v37, v39, v38, v18
	v_med3_f32 v38, v40, v39, v18
	v_med3_f32 v39, v41, v40, v18
	v_med3_f32 v40, v0, v41, v18
	v_max_f32_e32 v18, v18, v18
	v_max_f32_e32 v0, v0, v18
	v_or_b32_e32 v18, 0x51, v123
	v_and_or_b32 v18, v27, s88, v18
	v_med3_f32 v19, v20, v19, v18
	v_med3_f32 v20, v21, v20, v18
	v_med3_f32 v21, v22, v21, v18
	v_med3_f32 v22, v23, v22, v18
	v_med3_f32 v23, v24, v23, v18
	v_med3_f32 v24, v25, v24, v18
	v_med3_f32 v25, v26, v25, v18
	v_med3_f32 v26, v34, v26, v18
	v_med3_f32 v27, v35, v34, v18
	v_med3_f32 v34, v36, v35, v18
	v_med3_f32 v35, v37, v36, v18
	v_med3_f32 v36, v38, v37, v18
	v_med3_f32 v37, v39, v38, v18
	v_med3_f32 v38, v40, v39, v18
	v_med3_f32 v39, v0, v40, v18
	v_max_f32_e32 v18, v18, v18
	v_max_f32_e32 v0, v0, v18
	v_or_b32_e32 v18, 0x52, v123
	v_and_or_b32 v18, v28, s88, v18
	v_med3_f32 v19, v20, v19, v18
	v_med3_f32 v20, v21, v20, v18
	v_med3_f32 v21, v22, v21, v18
	v_med3_f32 v22, v23, v22, v18
	v_med3_f32 v23, v24, v23, v18
	v_med3_f32 v24, v25, v24, v18
	v_med3_f32 v25, v26, v25, v18
	v_med3_f32 v26, v27, v26, v18
	v_med3_f32 v27, v34, v27, v18
	v_med3_f32 v28, v35, v34, v18
	v_med3_f32 v34, v36, v35, v18
	v_med3_f32 v35, v37, v36, v18
	v_med3_f32 v36, v38, v37, v18
	v_med3_f32 v37, v39, v38, v18
	v_med3_f32 v38, v0, v39, v18
	v_max_f32_e32 v18, v18, v18
	v_max_f32_e32 v0, v0, v18
	v_or_b32_e32 v18, 0x53, v123
	v_and_or_b32 v18, v29, s88, v18
	v_med3_f32 v19, v20, v19, v18
	v_med3_f32 v20, v21, v20, v18
	v_med3_f32 v21, v22, v21, v18
	v_med3_f32 v22, v23, v22, v18
	v_med3_f32 v23, v24, v23, v18
	v_med3_f32 v24, v25, v24, v18
	v_med3_f32 v25, v26, v25, v18
	v_med3_f32 v26, v27, v26, v18
	v_med3_f32 v27, v28, v27, v18
	v_med3_f32 v28, v34, v28, v18
	v_med3_f32 v29, v35, v34, v18
	v_med3_f32 v34, v36, v35, v18
	v_med3_f32 v35, v37, v36, v18
	v_med3_f32 v36, v38, v37, v18
	v_med3_f32 v37, v0, v38, v18
	v_max_f32_e32 v18, v18, v18
	v_max_f32_e32 v0, v0, v18
	v_or_b32_e32 v18, 0x58, v123
	v_and_or_b32 v18, v30, s88, v18
	v_med3_f32 v19, v20, v19, v18
	v_med3_f32 v20, v21, v20, v18
	v_med3_f32 v21, v22, v21, v18
	v_med3_f32 v22, v23, v22, v18
	v_med3_f32 v23, v24, v23, v18
	v_med3_f32 v24, v25, v24, v18
	v_med3_f32 v25, v26, v25, v18
	v_med3_f32 v26, v27, v26, v18
	v_med3_f32 v27, v28, v27, v18
	v_med3_f32 v28, v29, v28, v18
	v_med3_f32 v29, v34, v29, v18
	v_med3_f32 v30, v35, v34, v18
	v_med3_f32 v34, v36, v35, v18
	v_med3_f32 v35, v37, v36, v18
	v_med3_f32 v36, v0, v37, v18
	v_max_f32_e32 v18, v18, v18
	v_max_f32_e32 v0, v0, v18
	v_or_b32_e32 v18, 0x59, v123
	v_and_or_b32 v18, v31, s88, v18
; DI void phase_peer_q(const Params& p, int layer, u16* lds, const int WAVE_S) {
;     ...
; #pragma unroll
;       for (int nt = 0; nt < 4; ++nt)
; #pragma unroll
;         for (int i = 0; i < 16; ++i) {
;           const uint32_t n = nt * 32 + (i & 3) + 8 * (i >> 2) + 4 * h;
;           const float v = __uint_as_float((__float_as_uint(acc[nt][0][i]) & ~127u) | n);
;           ins16n(t, v, nt * 16 + i);
;         }
	v_med3_f32 v19, v20, v19, v18
	v_med3_f32 v20, v21, v20, v18
	v_med3_f32 v21, v22, v21, v18
	v_med3_f32 v22, v23, v22, v18
	v_med3_f32 v23, v24, v23, v18
	v_med3_f32 v24, v25, v24, v18
	v_med3_f32 v25, v26, v25, v18
	v_med3_f32 v26, v27, v26, v18
	v_med3_f32 v27, v28, v27, v18
	v_med3_f32 v28, v29, v28, v18
	v_med3_f32 v29, v30, v29, v18
	v_med3_f32 v30, v34, v30, v18
	v_med3_f32 v31, v35, v34, v18
	v_med3_f32 v34, v36, v35, v18
	v_med3_f32 v35, v0, v36, v18
	v_max_f32_e32 v18, v18, v18
	v_max_f32_e32 v0, v0, v18
	v_or_b32_e32 v18, 0x5a, v123
	v_and_or_b32 v18, v32, s88, v18
	v_med3_f32 v19, v20, v19, v18
	v_med3_f32 v20, v21, v20, v18
	v_med3_f32 v21, v22, v21, v18
	v_med3_f32 v22, v23, v22, v18
	v_med3_f32 v23, v24, v23, v18
	v_med3_f32 v24, v25, v24, v18
	v_med3_f32 v25, v26, v25, v18
	v_med3_f32 v26, v27, v26, v18
	v_med3_f32 v27, v28, v27, v18
	v_med3_f32 v28, v29, v28, v18
	v_med3_f32 v29, v30, v29, v18
	v_med3_f32 v30, v31, v30, v18
	v_med3_f32 v31, v34, v31, v18
	v_med3_f32 v32, v35, v34, v18
	v_med3_f32 v34, v0, v35, v18
	v_max_f32_e32 v18, v18, v18
	v_max_f32_e32 v0, v0, v18
	v_or_b32_e32 v18, 0x5b, v123
	v_and_or_b32 v18, v33, s88, v18
	v_med3_f32 v19, v20, v19, v18
	v_med3_f32 v20, v21, v20, v18
	v_med3_f32 v21, v22, v21, v18
	v_med3_f32 v22, v23, v22, v18
	v_med3_f32 v23, v24, v23, v18
	v_med3_f32 v24, v25, v24, v18
	v_med3_f32 v25, v26, v25, v18
	v_med3_f32 v26, v27, v26, v18
	v_med3_f32 v27, v28, v27, v18
	v_med3_f32 v28, v29, v28, v18
	v_med3_f32 v29, v30, v29, v18
	v_med3_f32 v30, v31, v30, v18
	v_med3_f32 v31, v32, v31, v18
	v_med3_f32 v32, v34, v32, v18
	v_med3_f32 v33, v0, v34, v18
	v_max_f32_e32 v18, v18, v18
	v_max_f32_e32 v0, v0, v18
	v_or_b32_e32 v18, 0x60, v123
	v_and_or_b32 v2, v2, s88, v18
	v_med3_f32 v18, v20, v19, v2
	v_med3_f32 v19, v21, v20, v2
	v_med3_f32 v20, v22, v21, v2
	v_med3_f32 v21, v23, v22, v2
	v_med3_f32 v22, v24, v23, v2
	v_med3_f32 v23, v25, v24, v2
	v_med3_f32 v24, v26, v25, v2
	v_med3_f32 v25, v27, v26, v2
	v_med3_f32 v26, v28, v27, v2
	v_med3_f32 v27, v29, v28, v2
	v_med3_f32 v28, v30, v29, v2
	v_med3_f32 v29, v31, v30, v2
	v_med3_f32 v30, v32, v31, v2
	v_med3_f32 v31, v33, v32, v2
	v_med3_f32 v32, v0, v33, v2
	v_max_f32_e32 v2, v2, v2
	v_max_f32_e32 v0, v0, v2
	v_or_b32_e32 v2, 0x61, v123
	v_and_or_b32 v2, v3, s88, v2
	v_med3_f32 v3, v19, v18, v2
	v_med3_f32 v18, v20, v19, v2
	v_med3_f32 v19, v21, v20, v2
	v_med3_f32 v20, v22, v21, v2
	v_med3_f32 v21, v23, v22, v2
	v_med3_f32 v22, v24, v23, v2
	v_med3_f32 v23, v25, v24, v2
	v_med3_f32 v24, v26, v25, v2
	v_med3_f32 v25, v27, v26, v2
	v_med3_f32 v26, v28, v27, v2
	v_med3_f32 v27, v29, v28, v2
	v_med3_f32 v28, v30, v29, v2
	v_med3_f32 v29, v31, v30, v2
	v_med3_f32 v30, v32, v31, v2
	v_med3_f32 v31, v0, v32, v2
	v_max_f32_e32 v2, v2, v2
	v_max_f32_e32 v0, v0, v2
	v_or_b32_e32 v2, 0x62, v123
	v_and_or_b32 v2, v4, s88, v2
	v_med3_f32 v3, v18, v3, v2
	v_med3_f32 v4, v19, v18, v2
	v_med3_f32 v18, v20, v19, v2
	v_med3_f32 v19, v21, v20, v2
	v_med3_f32 v20, v22, v21, v2
	v_med3_f32 v21, v23, v22, v2
	v_med3_f32 v22, v24, v23, v2
	v_med3_f32 v23, v25, v24, v2
	v_med3_f32 v24, v26, v25, v2
	v_med3_f32 v25, v27, v26, v2
	v_med3_f32 v26, v28, v27, v2
	v_med3_f32 v27, v29, v28, v2
	v_med3_f32 v28, v30, v29, v2
	v_med3_f32 v29, v31, v30, v2
	v_med3_f32 v30, v0, v31, v2
	v_max_f32_e32 v2, v2, v2
	v_max_f32_e32 v0, v0, v2
	v_or_b32_e32 v2, 0x63, v123
	v_and_or_b32 v2, v5, s88, v2
	v_med3_f32 v3, v4, v3, v2
	v_med3_f32 v4, v18, v4, v2
	v_med3_f32 v5, v19, v18, v2
	v_med3_f32 v18, v20, v19, v2
	v_med3_f32 v19, v21, v20, v2
	v_med3_f32 v20, v22, v21, v2
	v_med3_f32 v21, v23, v22, v2
	v_med3_f32 v22, v24, v23, v2
	v_med3_f32 v23, v25, v24, v2
	v_med3_f32 v24, v26, v25, v2
	v_med3_f32 v25, v27, v26, v2
	v_med3_f32 v26, v28, v27, v2
	v_med3_f32 v27, v29, v28, v2
	v_med3_f32 v28, v30, v29, v2
	v_med3_f32 v29, v0, v30, v2
	v_max_f32_e32 v2, v2, v2
	v_max_f32_e32 v0, v0, v2
	v_or_b32_e32 v2, 0x68, v123
	v_and_or_b32 v2, v6, s88, v2
	v_med3_f32 v3, v4, v3, v2
	v_med3_f32 v4, v5, v4, v2
	v_med3_f32 v5, v18, v5, v2
	v_med3_f32 v6, v19, v18, v2
	v_med3_f32 v18, v20, v19, v2
	v_med3_f32 v19, v21, v20, v2
	v_med3_f32 v20, v22, v21, v2
	v_med3_f32 v21, v23, v22, v2
	v_med3_f32 v22, v24, v23, v2
	v_med3_f32 v23, v25, v24, v2
	v_med3_f32 v24, v26, v25, v2
	v_med3_f32 v25, v27, v26, v2
	v_med3_f32 v26, v28, v27, v2
	v_med3_f32 v27, v29, v28, v2
	v_med3_f32 v28, v0, v29, v2
	v_max_f32_e32 v2, v2, v2
	v_max_f32_e32 v0, v0, v2
	v_or_b32_e32 v2, 0x69, v123
	v_and_or_b32 v2, v7, s88, v2
	v_med3_f32 v3, v4, v3, v2
	v_med3_f32 v4, v5, v4, v2
	v_med3_f32 v5, v6, v5, v2
	v_med3_f32 v6, v18, v6, v2
	v_med3_f32 v7, v19, v18, v2
	v_med3_f32 v18, v20, v19, v2
	v_med3_f32 v19, v21, v20, v2
	v_med3_f32 v20, v22, v21, v2
	v_med3_f32 v21, v23, v22, v2
	v_med3_f32 v22, v24, v23, v2
	v_med3_f32 v23, v25, v24, v2
	v_med3_f32 v24, v26, v25, v2
	v_med3_f32 v25, v27, v26, v2
	v_med3_f32 v26, v28, v27, v2
	v_med3_f32 v27, v0, v28, v2
	v_max_f32_e32 v2, v2, v2
	v_max_f32_e32 v0, v0, v2
	v_or_b32_e32 v2, 0x6a, v123
	v_and_or_b32 v2, v8, s88, v2
	v_med3_f32 v3, v4, v3, v2
	v_med3_f32 v4, v5, v4, v2
	v_med3_f32 v5, v6, v5, v2
	v_med3_f32 v6, v7, v6, v2
	v_med3_f32 v7, v18, v7, v2
	v_med3_f32 v8, v19, v18, v2
	v_med3_f32 v18, v20, v19, v2
	v_med3_f32 v19, v21, v20, v2
	v_med3_f32 v20, v22, v21, v2
	v_med3_f32 v21, v23, v22, v2
	v_med3_f32 v22, v24, v23, v2
	v_med3_f32 v23, v25, v24, v2
	v_med3_f32 v24, v26, v25, v2
	v_med3_f32 v25, v27, v26, v2
	v_med3_f32 v26, v0, v27, v2
	v_max_f32_e32 v2, v2, v2
	v_max_f32_e32 v0, v0, v2
	v_or_b32_e32 v2, 0x6b, v123
	v_and_or_b32 v2, v9, s88, v2
	v_med3_f32 v3, v4, v3, v2
; DI void phase_peer_q(const Params& p, int layer, u16* lds, const int WAVE_S) {
;     ...
; #pragma unroll
;       for (int nt = 0; nt < 4; ++nt)
; #pragma unroll
;         for (int i = 0; i < 16; ++i) {
;           const uint32_t n = nt * 32 + (i & 3) + 8 * (i >> 2) + 4 * h;
;           const float v = __uint_as_float((__float_as_uint(acc[nt][0][i]) & ~127u) | n);
;           ins16n(t, v, nt * 16 + i);
;         }
;       float o16[16];
; #pragma unroll
;       for (int i = 0; i < 16; ++i) {
;         auto rr = __builtin_amdgcn_permlane32_swap(__float_as_uint(t[i]), __float_as_uint(t[i]), false, false);
;         o16[i] = __uint_as_float(h ? rr[0] : rr[1]);
;       }
	v_med3_f32 v4, v5, v4, v2
	v_med3_f32 v5, v6, v5, v2
	v_med3_f32 v6, v7, v6, v2
	v_med3_f32 v7, v8, v7, v2
	v_med3_f32 v8, v18, v8, v2
	v_med3_f32 v9, v19, v18, v2
	v_med3_f32 v18, v20, v19, v2
	v_med3_f32 v19, v21, v20, v2
	v_med3_f32 v20, v22, v21, v2
	v_med3_f32 v21, v23, v22, v2
	v_med3_f32 v22, v24, v23, v2
	v_med3_f32 v23, v25, v24, v2
	v_med3_f32 v24, v26, v25, v2
	v_med3_f32 v25, v0, v26, v2
	v_max_f32_e32 v2, v2, v2
	v_max_f32_e32 v0, v0, v2
	v_and_or_b32 v2, v10, s88, v125
	v_med3_f32 v3, v4, v3, v2
	v_med3_f32 v4, v5, v4, v2
	v_med3_f32 v5, v6, v5, v2
	v_med3_f32 v6, v7, v6, v2
	v_med3_f32 v7, v8, v7, v2
	v_med3_f32 v8, v9, v8, v2
	v_med3_f32 v9, v18, v9, v2
	v_med3_f32 v10, v19, v18, v2
	v_med3_f32 v18, v20, v19, v2
	v_med3_f32 v19, v21, v20, v2
	v_med3_f32 v20, v22, v21, v2
	v_med3_f32 v21, v23, v22, v2
	v_med3_f32 v22, v24, v23, v2
	v_med3_f32 v23, v25, v24, v2
	v_med3_f32 v24, v0, v25, v2
	v_max_f32_e32 v2, v2, v2
	v_max_f32_e32 v0, v0, v2
	v_and_or_b32 v2, v11, s88, v126
	v_med3_f32 v3, v4, v3, v2
	v_med3_f32 v4, v5, v4, v2
	v_med3_f32 v5, v6, v5, v2
	v_med3_f32 v6, v7, v6, v2
	v_med3_f32 v7, v8, v7, v2
	v_med3_f32 v8, v9, v8, v2
	v_med3_f32 v9, v10, v9, v2
	v_med3_f32 v10, v18, v10, v2
	v_med3_f32 v11, v19, v18, v2
	v_med3_f32 v18, v20, v19, v2
	v_med3_f32 v19, v21, v20, v2
	v_med3_f32 v20, v22, v21, v2
	v_med3_f32 v21, v23, v22, v2
	v_med3_f32 v22, v24, v23, v2
	v_med3_f32 v23, v0, v24, v2
	v_max_f32_e32 v2, v2, v2
	v_max_f32_e32 v0, v0, v2
	v_and_or_b32 v2, v12, s88, v127
	v_med3_f32 v3, v4, v3, v2
	v_med3_f32 v4, v5, v4, v2
	v_med3_f32 v5, v6, v5, v2
	v_med3_f32 v6, v7, v6, v2
	v_med3_f32 v7, v8, v7, v2
	v_med3_f32 v8, v9, v8, v2
	v_med3_f32 v9, v10, v9, v2
	v_med3_f32 v10, v11, v10, v2
	v_med3_f32 v11, v18, v11, v2
	v_med3_f32 v12, v19, v18, v2
	v_med3_f32 v18, v20, v19, v2
	v_med3_f32 v19, v21, v20, v2
	v_med3_f32 v20, v22, v21, v2
	v_med3_f32 v21, v23, v22, v2
	v_med3_f32 v22, v0, v23, v2
	v_max_f32_e32 v2, v2, v2
	v_max_f32_e32 v0, v0, v2
	v_and_or_b32 v2, v13, s88, v128
	v_med3_f32 v3, v4, v3, v2
	v_med3_f32 v4, v5, v4, v2
	v_med3_f32 v5, v6, v5, v2
	v_med3_f32 v6, v7, v6, v2
	v_med3_f32 v7, v8, v7, v2
	v_med3_f32 v8, v9, v8, v2
	v_med3_f32 v9, v10, v9, v2
	v_med3_f32 v10, v11, v10, v2
	v_med3_f32 v11, v12, v11, v2
	v_med3_f32 v12, v18, v12, v2
	v_med3_f32 v13, v19, v18, v2
	v_med3_f32 v18, v20, v19, v2
	v_med3_f32 v19, v21, v20, v2
	v_med3_f32 v20, v22, v21, v2
	v_med3_f32 v21, v0, v22, v2
	v_max_f32_e32 v2, v2, v2
	v_max_f32_e32 v0, v0, v2
	v_and_or_b32 v2, v14, s88, v129
	v_med3_f32 v3, v4, v3, v2
	v_med3_f32 v4, v5, v4, v2
	v_med3_f32 v5, v6, v5, v2
	v_med3_f32 v6, v7, v6, v2
	v_med3_f32 v7, v8, v7, v2
	v_med3_f32 v8, v9, v8, v2
	v_med3_f32 v9, v10, v9, v2
	v_med3_f32 v10, v11, v10, v2
	v_med3_f32 v11, v12, v11, v2
	v_med3_f32 v12, v13, v12, v2
	v_med3_f32 v13, v18, v13, v2
	v_med3_f32 v14, v19, v18, v2
	v_med3_f32 v18, v20, v19, v2
	v_med3_f32 v19, v21, v20, v2
	v_med3_f32 v20, v0, v21, v2
	v_max_f32_e32 v2, v2, v2
	v_max_f32_e32 v0, v0, v2
	v_and_or_b32 v2, v15, s88, v130
	v_med3_f32 v3, v4, v3, v2
	v_med3_f32 v4, v5, v4, v2
	v_med3_f32 v5, v6, v5, v2
	v_med3_f32 v6, v7, v6, v2
	v_med3_f32 v7, v8, v7, v2
	v_med3_f32 v8, v9, v8, v2
	v_med3_f32 v9, v10, v9, v2
	v_med3_f32 v10, v11, v10, v2
	v_med3_f32 v11, v12, v11, v2
	v_med3_f32 v12, v13, v12, v2
	v_med3_f32 v13, v14, v13, v2
	v_med3_f32 v14, v18, v14, v2
	v_med3_f32 v15, v19, v18, v2
	v_med3_f32 v18, v20, v19, v2
	v_med3_f32 v19, v0, v20, v2
	v_max_f32_e32 v2, v2, v2
	v_max_f32_e32 v0, v0, v2
	v_and_or_b32 v2, v16, s88, v131
	v_med3_f32 v3, v4, v3, v2
	v_med3_f32 v4, v5, v4, v2
	v_med3_f32 v5, v6, v5, v2
	v_med3_f32 v6, v7, v6, v2
	v_med3_f32 v7, v8, v7, v2
	v_med3_f32 v8, v9, v8, v2
	v_med3_f32 v9, v10, v9, v2
	v_med3_f32 v10, v11, v10, v2
	v_med3_f32 v11, v12, v11, v2
	v_med3_f32 v12, v13, v12, v2
	v_med3_f32 v13, v14, v13, v2
	v_med3_f32 v14, v15, v14, v2
	v_med3_f32 v15, v18, v15, v2
	v_med3_f32 v16, v19, v18, v2
	v_med3_f32 v18, v0, v19, v2
	v_max_f32_e32 v2, v2, v2
	v_max_f32_e32 v0, v0, v2
	v_and_or_b32 v2, v17, s88, v132
	v_med3_f32 v3, v4, v3, v2
	v_med3_f32 v4, v5, v4, v2
	v_med3_f32 v5, v6, v5, v2
	v_med3_f32 v6, v7, v6, v2
	v_med3_f32 v7, v8, v7, v2
	v_med3_f32 v8, v9, v8, v2
	v_med3_f32 v9, v10, v9, v2
	v_med3_f32 v10, v11, v10, v2
	v_med3_f32 v11, v12, v11, v2
	v_med3_f32 v12, v13, v12, v2
	v_med3_f32 v13, v14, v13, v2
	v_med3_f32 v14, v15, v14, v2
	v_med3_f32 v15, v16, v15, v2
	v_med3_f32 v16, v18, v16, v2
	v_med3_f32 v17, v0, v18, v2
	v_max_f32_e32 v2, v2, v2
	v_max_f32_e32 v0, v0, v2
	v_mov_b32_e32 v2, v0
	v_mov_b32_e32 v18, v0
	s_nop 1
	v_permlane32_swap_b32_e32 v2, v18
	v_cndmask_b32_e64 v2, v2, v18, s[34:35]
	v_mov_b32_e32 v18, v17
	v_mov_b32_e32 v19, v17
	s_nop 1
	v_permlane32_swap_b32_e32 v18, v19
	v_cndmask_b32_e64 v18, v18, v19, s[34:35]
	v_mov_b32_e32 v19, v16
	v_mov_b32_e32 v20, v16
	s_nop 1
	v_permlane32_swap_b32_e32 v19, v20
	v_cndmask_b32_e64 v19, v19, v20, s[34:35]
	v_mov_b32_e32 v20, v15
	v_mov_b32_e32 v21, v15
	s_nop 1
	v_permlane32_swap_b32_e32 v20, v21
	v_cndmask_b32_e64 v20, v20, v21, s[34:35]
	v_mov_b32_e32 v21, v14
	v_mov_b32_e32 v22, v14
	s_nop 1
	v_permlane32_swap_b32_e32 v21, v22
	v_cndmask_b32_e64 v21, v21, v22, s[34:35]
	v_mov_b32_e32 v22, v13
	v_mov_b32_e32 v23, v13
	s_nop 1
	v_permlane32_swap_b32_e32 v22, v23
	v_cndmask_b32_e64 v22, v22, v23, s[34:35]
	v_mov_b32_e32 v23, v12
	v_mov_b32_e32 v24, v12
	s_nop 1
	v_permlane32_swap_b32_e32 v23, v24
	v_cndmask_b32_e64 v23, v23, v24, s[34:35]
	v_mov_b32_e32 v24, v11
	v_mov_b32_e32 v25, v11
	s_nop 1
	v_permlane32_swap_b32_e32 v24, v25
	v_cndmask_b32_e64 v24, v24, v25, s[34:35]
; DI void phase_peer_q(const Params& p, int layer, u16* lds, const int WAVE_S) {
;     ...
;       float o16[16];
; #pragma unroll
;       for (int i = 0; i < 16; ++i) {
;         auto rr = __builtin_amdgcn_permlane32_swap(__float_as_uint(t[i]), __float_as_uint(t[i]), false, false);
;         o16[i] = __uint_as_float(h ? rr[0] : rr[1]);
;       }
; #pragma unroll
;       for (int i = 0; i < 16; ++i) ins16(t, o16[i]);
	v_mov_b32_e32 v25, v10
	v_mov_b32_e32 v26, v10
	s_nop 1
	v_permlane32_swap_b32_e32 v25, v26
	v_cndmask_b32_e64 v25, v25, v26, s[34:35]
	v_mov_b32_e32 v26, v9
	v_mov_b32_e32 v27, v9
	s_nop 1
	v_permlane32_swap_b32_e32 v26, v27
	v_cndmask_b32_e64 v26, v26, v27, s[34:35]
	v_mov_b32_e32 v27, v8
	v_mov_b32_e32 v28, v8
	s_nop 1
	v_permlane32_swap_b32_e32 v27, v28
	v_cndmask_b32_e64 v27, v27, v28, s[34:35]
	v_mov_b32_e32 v28, v7
	v_mov_b32_e32 v29, v7
	s_nop 1
	v_permlane32_swap_b32_e32 v28, v29
	v_cndmask_b32_e64 v28, v28, v29, s[34:35]
	v_mov_b32_e32 v29, v6
	v_mov_b32_e32 v30, v6
	s_nop 1
	v_permlane32_swap_b32_e32 v29, v30
	v_cndmask_b32_e64 v29, v29, v30, s[34:35]
	v_mov_b32_e32 v30, v5
	v_mov_b32_e32 v31, v5
	s_nop 1
	v_permlane32_swap_b32_e32 v30, v31
	v_cndmask_b32_e64 v30, v30, v31, s[34:35]
	v_mov_b32_e32 v31, v4
	v_mov_b32_e32 v32, v4
	s_nop 1
	v_permlane32_swap_b32_e32 v31, v32
	v_cndmask_b32_e64 v31, v31, v32, s[34:35]
	v_mov_b32_e32 v32, v3
	v_mov_b32_e32 v33, v3
	v_med3_f32 v3, v4, v3, v2
	v_med3_f32 v4, v5, v4, v2
	v_med3_f32 v5, v6, v5, v2
	v_med3_f32 v6, v7, v6, v2
	v_med3_f32 v7, v8, v7, v2
	v_med3_f32 v8, v9, v8, v2
	v_med3_f32 v9, v10, v9, v2
	v_med3_f32 v10, v11, v10, v2
	v_med3_f32 v11, v12, v11, v2
	v_med3_f32 v12, v13, v12, v2
	v_med3_f32 v13, v14, v13, v2
	v_med3_f32 v14, v15, v14, v2
	v_med3_f32 v15, v16, v15, v2
	v_med3_f32 v16, v17, v16, v2
	v_med3_f32 v17, v0, v17, v2
	v_max_f32_e32 v2, v2, v2
	v_max_f32_e32 v0, v0, v2
	v_med3_f32 v2, v4, v3, v18
	v_med3_f32 v3, v5, v4, v18
	v_med3_f32 v4, v6, v5, v18
	v_med3_f32 v5, v7, v6, v18
	v_med3_f32 v6, v8, v7, v18
	v_med3_f32 v7, v9, v8, v18
	v_med3_f32 v8, v10, v9, v18
	v_med3_f32 v9, v11, v10, v18
	v_med3_f32 v10, v12, v11, v18
	v_med3_f32 v11, v13, v12, v18
	v_med3_f32 v12, v14, v13, v18
	v_med3_f32 v13, v15, v14, v18
	v_med3_f32 v14, v16, v15, v18
	v_med3_f32 v15, v17, v16, v18
	v_med3_f32 v16, v0, v17, v18
	v_max_f32_e32 v17, v18, v18
	v_max_f32_e32 v0, v0, v17
	v_max_f32_e32 v17, v19, v19
	v_med3_f32 v2, v3, v2, v19
	v_med3_f32 v3, v4, v3, v19
	v_med3_f32 v4, v5, v4, v19
	v_med3_f32 v5, v6, v5, v19
	v_med3_f32 v6, v7, v6, v19
	v_med3_f32 v7, v8, v7, v19
	v_med3_f32 v8, v9, v8, v19
	v_med3_f32 v9, v10, v9, v19
	v_med3_f32 v10, v11, v10, v19
	v_med3_f32 v11, v12, v11, v19
	v_med3_f32 v12, v13, v12, v19
	v_med3_f32 v13, v14, v13, v19
	v_med3_f32 v14, v15, v14, v19
	v_med3_f32 v15, v16, v15, v19
	v_med3_f32 v16, v0, v16, v19
	v_max_f32_e32 v0, v0, v17
	v_max_f32_e32 v17, v20, v20
	v_med3_f32 v2, v3, v2, v20
	v_med3_f32 v3, v4, v3, v20
	v_med3_f32 v4, v5, v4, v20
	v_med3_f32 v5, v6, v5, v20
	v_med3_f32 v6, v7, v6, v20
	v_med3_f32 v7, v8, v7, v20
	v_med3_f32 v8, v9, v8, v20
	v_med3_f32 v9, v10, v9, v20
	v_med3_f32 v10, v11, v10, v20
	v_med3_f32 v11, v12, v11, v20
	v_med3_f32 v12, v13, v12, v20
	v_med3_f32 v13, v14, v13, v20
	v_med3_f32 v14, v15, v14, v20
	v_med3_f32 v15, v16, v15, v20
	v_med3_f32 v16, v0, v16, v20
	v_max_f32_e32 v0, v0, v17
	v_max_f32_e32 v17, v21, v21
	v_med3_f32 v2, v3, v2, v21
	v_med3_f32 v3, v4, v3, v21
	v_med3_f32 v4, v5, v4, v21
	v_med3_f32 v5, v6, v5, v21
	v_med3_f32 v6, v7, v6, v21
	v_med3_f32 v7, v8, v7, v21
	v_med3_f32 v8, v9, v8, v21
	v_med3_f32 v9, v10, v9, v21
	v_med3_f32 v10, v11, v10, v21
	v_med3_f32 v11, v12, v11, v21
	v_med3_f32 v12, v13, v12, v21
	v_med3_f32 v13, v14, v13, v21
	v_med3_f32 v14, v15, v14, v21
	v_med3_f32 v15, v16, v15, v21
	v_med3_f32 v16, v0, v16, v21
	v_max_f32_e32 v0, v0, v17
	v_max_f32_e32 v17, v22, v22
	v_med3_f32 v2, v3, v2, v22
	v_med3_f32 v3, v4, v3, v22
	v_med3_f32 v4, v5, v4, v22
	v_med3_f32 v5, v6, v5, v22
	v_med3_f32 v6, v7, v6, v22
	v_med3_f32 v7, v8, v7, v22
	v_med3_f32 v8, v9, v8, v22
	v_med3_f32 v9, v10, v9, v22
	v_med3_f32 v10, v11, v10, v22
	v_med3_f32 v11, v12, v11, v22
	v_med3_f32 v12, v13, v12, v22
	v_med3_f32 v13, v14, v13, v22
	v_med3_f32 v14, v15, v14, v22
	v_med3_f32 v15, v16, v15, v22
	v_med3_f32 v16, v0, v16, v22
	v_max_f32_e32 v0, v0, v17
	v_max_f32_e32 v17, v23, v23
	v_med3_f32 v2, v3, v2, v23
	v_med3_f32 v3, v4, v3, v23
	v_med3_f32 v4, v5, v4, v23
	v_med3_f32 v5, v6, v5, v23
	v_med3_f32 v6, v7, v6, v23
	v_med3_f32 v7, v8, v7, v23
	v_med3_f32 v8, v9, v8, v23
	v_med3_f32 v9, v10, v9, v23
	v_med3_f32 v10, v11, v10, v23
	v_med3_f32 v11, v12, v11, v23
	v_med3_f32 v12, v13, v12, v23
	v_med3_f32 v13, v14, v13, v23
	v_med3_f32 v14, v15, v14, v23
	v_med3_f32 v15, v16, v15, v23
	v_med3_f32 v16, v0, v16, v23
	v_max_f32_e32 v0, v0, v17
	v_max_f32_e32 v17, v24, v24
	v_med3_f32 v2, v3, v2, v24
	v_med3_f32 v3, v4, v3, v24
	v_med3_f32 v4, v5, v4, v24
	v_med3_f32 v5, v6, v5, v24
	v_med3_f32 v6, v7, v6, v24
	v_med3_f32 v7, v8, v7, v24
	v_med3_f32 v8, v9, v8, v24
; DI void phase_peer_q(const Params& p, int layer, u16* lds, const int WAVE_S) {
;     ...
;       float o16[16];
; #pragma unroll
;       for (int i = 0; i < 16; ++i) {
;         auto rr = __builtin_amdgcn_permlane32_swap(__float_as_uint(t[i]), __float_as_uint(t[i]), false, false);
;         o16[i] = __uint_as_float(h ? rr[0] : rr[1]);
;       }
; #pragma unroll
;       for (int i = 0; i < 16; ++i) ins16(t, o16[i]);
;       if (half == 0) {
; #pragma unroll
;         for (int i = 0; i < 16; ++i) t0[i] = t[i];
;       }
;     }
	v_med3_f32 v9, v10, v9, v24
	v_med3_f32 v10, v11, v10, v24
	v_med3_f32 v11, v12, v11, v24
	v_med3_f32 v12, v13, v12, v24
	v_med3_f32 v13, v14, v13, v24
	v_med3_f32 v14, v15, v14, v24
	v_med3_f32 v15, v16, v15, v24
	v_med3_f32 v16, v0, v16, v24
	v_max_f32_e32 v0, v0, v17
	v_med3_f32 v2, v3, v2, v25
	v_med3_f32 v3, v4, v3, v25
	v_med3_f32 v4, v5, v4, v25
	v_med3_f32 v5, v6, v5, v25
	v_med3_f32 v6, v7, v6, v25
	v_med3_f32 v7, v8, v7, v25
	v_med3_f32 v8, v9, v8, v25
	v_med3_f32 v9, v10, v9, v25
	v_med3_f32 v10, v11, v10, v25
	v_med3_f32 v11, v12, v11, v25
	v_med3_f32 v12, v13, v12, v25
	v_med3_f32 v13, v14, v13, v25
	v_med3_f32 v14, v15, v14, v25
	v_med3_f32 v15, v16, v15, v25
	v_med3_f32 v16, v0, v16, v25
	v_max_f32_e32 v17, v25, v25
	v_max_f32_e32 v0, v0, v17
	v_med3_f32 v2, v3, v2, v26
	v_med3_f32 v3, v4, v3, v26
	v_med3_f32 v4, v5, v4, v26
	v_med3_f32 v5, v6, v5, v26
	v_med3_f32 v6, v7, v6, v26
	v_med3_f32 v7, v8, v7, v26
	v_med3_f32 v8, v9, v8, v26
	v_med3_f32 v9, v10, v9, v26
	v_med3_f32 v10, v11, v10, v26
	v_med3_f32 v11, v12, v11, v26
	v_med3_f32 v12, v13, v12, v26
	v_med3_f32 v13, v14, v13, v26
	v_med3_f32 v14, v15, v14, v26
	v_med3_f32 v15, v16, v15, v26
	v_max_f32_e32 v17, v26, v26
	v_med3_f32 v16, v0, v16, v26
	v_max_f32_e32 v0, v0, v17
	v_med3_f32 v2, v3, v2, v27
	v_med3_f32 v3, v4, v3, v27
	v_med3_f32 v4, v5, v4, v27
	v_med3_f32 v5, v6, v5, v27
	v_med3_f32 v6, v7, v6, v27
	v_med3_f32 v7, v8, v7, v27
	v_med3_f32 v8, v9, v8, v27
	v_med3_f32 v9, v10, v9, v27
	v_med3_f32 v10, v11, v10, v27
	v_med3_f32 v11, v12, v11, v27
	v_med3_f32 v12, v13, v12, v27
	v_med3_f32 v13, v14, v13, v27
	v_med3_f32 v14, v15, v14, v27
	v_max_f32_e32 v17, v27, v27
	v_med3_f32 v15, v16, v15, v27
	v_med3_f32 v16, v0, v16, v27
	v_max_f32_e32 v0, v0, v17
	v_med3_f32 v2, v3, v2, v28
	v_med3_f32 v3, v4, v3, v28
	v_med3_f32 v4, v5, v4, v28
	v_med3_f32 v5, v6, v5, v28
	v_med3_f32 v6, v7, v6, v28
	v_med3_f32 v7, v8, v7, v28
	v_med3_f32 v8, v9, v8, v28
	v_med3_f32 v9, v10, v9, v28
	v_med3_f32 v10, v11, v10, v28
	v_med3_f32 v11, v12, v11, v28
	v_med3_f32 v12, v13, v12, v28
	v_med3_f32 v13, v14, v13, v28
	v_max_f32_e32 v17, v28, v28
	v_med3_f32 v14, v15, v14, v28
	v_med3_f32 v15, v16, v15, v28
	v_med3_f32 v16, v0, v16, v28
	v_max_f32_e32 v0, v0, v17
	v_med3_f32 v2, v3, v2, v29
	v_med3_f32 v3, v4, v3, v29
	v_med3_f32 v4, v5, v4, v29
	v_med3_f32 v5, v6, v5, v29
	v_med3_f32 v6, v7, v6, v29
	v_med3_f32 v7, v8, v7, v29
	v_med3_f32 v8, v9, v8, v29
	v_med3_f32 v9, v10, v9, v29
	v_med3_f32 v10, v11, v10, v29
	v_med3_f32 v11, v12, v11, v29
	v_med3_f32 v12, v13, v12, v29
	v_max_f32_e32 v17, v29, v29
	v_permlane32_swap_b32_e32 v32, v33
	v_med3_f32 v13, v14, v13, v29
	v_med3_f32 v14, v15, v14, v29
	v_med3_f32 v15, v16, v15, v29
	v_med3_f32 v16, v0, v16, v29
	v_max_f32_e32 v0, v0, v17
	v_med3_f32 v2, v3, v2, v30
	v_med3_f32 v3, v4, v3, v30
	v_med3_f32 v4, v5, v4, v30
	v_med3_f32 v5, v6, v5, v30
	v_med3_f32 v6, v7, v6, v30
	v_med3_f32 v7, v8, v7, v30
	v_med3_f32 v8, v9, v8, v30
	v_med3_f32 v9, v10, v9, v30
	v_med3_f32 v10, v11, v10, v30
	v_med3_f32 v11, v12, v11, v30
	v_max_f32_e32 v17, v30, v30
	v_cndmask_b32_e64 v32, v32, v33, s[34:35]
	v_med3_f32 v12, v13, v12, v30
	v_med3_f32 v13, v14, v13, v30
	v_med3_f32 v14, v15, v14, v30
	v_med3_f32 v15, v16, v15, v30
	v_med3_f32 v16, v0, v16, v30
	v_max_f32_e32 v0, v0, v17
	v_med3_f32 v2, v3, v2, v31
	v_med3_f32 v3, v4, v3, v31
	v_med3_f32 v4, v5, v4, v31
	v_med3_f32 v5, v6, v5, v31
	v_med3_f32 v6, v7, v6, v31
	v_med3_f32 v7, v8, v7, v31
	v_med3_f32 v8, v9, v8, v31
	v_med3_f32 v9, v10, v9, v31
	v_med3_f32 v18, v11, v10, v31
	v_max_f32_e32 v10, v31, v31
	v_med3_f32 v19, v12, v11, v31
	v_med3_f32 v20, v13, v12, v31
	v_med3_f32 v21, v14, v13, v31
	v_med3_f32 v22, v15, v14, v31
	v_med3_f32 v23, v16, v15, v31
	v_med3_f32 v24, v0, v16, v31
	v_max_f32_e32 v0, v0, v10
	v_med3_f32 v11, v3, v2, v32
	v_max_f32_e32 v2, v32, v32
	v_med3_f32 v10, v4, v3, v32
	v_med3_f32 v13, v5, v4, v32
	v_med3_f32 v12, v6, v5, v32
	v_med3_f32 v15, v7, v6, v32
	v_med3_f32 v14, v8, v7, v32
	v_med3_f32 v17, v9, v8, v32
	v_med3_f32 v16, v18, v9, v32
	v_med3_f32 v9, v19, v18, v32
	v_med3_f32 v8, v20, v19, v32
	v_med3_f32 v7, v21, v20, v32
	v_med3_f32 v6, v22, v21, v32
	v_med3_f32 v5, v23, v22, v32
	v_med3_f32 v4, v24, v23, v32
	v_med3_f32 v3, v0, v24, v32
	v_max_f32_e32 v2, v0, v2
	s_cbranch_vccz .LBB0_388
	v_mov_b64_e32 v[18:19], v[98:99]
	v_mov_b64_e32 v[20:21], v[100:101]
	v_mov_b64_e32 v[22:23], v[102:103]
	v_mov_b64_e32 v[24:25], v[104:105]
	v_mov_b64_e32 v[26:27], v[106:107]
	v_mov_b64_e32 v[28:29], v[108:109]
	v_mov_b64_e32 v[30:31], v[110:111]
	v_mov_b64_e32 v[32:33], v[112:113]
	s_branch .LBB0_389
